# nt hint on cold single-use streams: w_ada and f32 weight reads (phase0/0b), x reads in norm1 and w_out epilogue, final output stores
# speedup vs baseline: 1.0322x; 1.0230x over previous
.LBB0_6:
	s_or_b64 exec, exec, s[2:3]
	v_mul_u32_u24_e32 v150, 0xaab, v1
	v_lshrrev_b32_e32 v150, 16, v150
	v_mul_u32_u24_e32 v151, 24, v150
	v_sub_u32_e32 v151, v1, v151
	v_mul_u32_u24_e32 v166, 0x6000, v150
	v_lshl_add_u32 v166, v151, 2, v166
	s_and_b32 s4, s80, 7
	s_lshl_b32 s4, s4, 5
	s_lshr_b32 s5, s80, 3
	s_or_b32 s4, s4, s5
	s_cmpk_lg_i32 s76, 0x100
	s_cselect_b32 s4, s80, s4
	s_mul_i32 s4, s4, 0x60
	v_lshl_add_u32 v152, v151, 2, s4
	global_load_dword v149, v152, s[100:101] nt
	s_add_u32 s100, s98, s4
	s_addc_u32 s101, s99, 0
	global_load_dword v100, v166, s[100:101] nt
	s_add_u32 s100, s100, 0x7e000
	s_addc_u32 s101, s101, 0
	global_load_dword v101, v166, s[100:101] nt
	s_add_u32 s100, s100, 0x7e000
	s_addc_u32 s101, s101, 0
	global_load_dword v102, v166, s[100:101] nt
	s_add_u32 s100, s100, 0x7e000
	s_addc_u32 s101, s101, 0
	global_load_dword v103, v166, s[100:101] nt
	s_add_u32 s100, s100, 0x7e000
	s_addc_u32 s101, s101, 0
	global_load_dword v104, v166, s[100:101] nt
	s_add_u32 s100, s100, 0x7e000
	s_addc_u32 s101, s101, 0
	global_load_dword v105, v166, s[100:101] nt
	s_add_u32 s100, s100, 0x7e000
	s_addc_u32 s101, s101, 0
	global_load_dword v106, v166, s[100:101] nt
	s_add_u32 s100, s100, 0x7e000
	s_addc_u32 s101, s101, 0
	global_load_dword v107, v166, s[100:101] nt
	s_add_u32 s100, s100, 0x7e000
	s_addc_u32 s101, s101, 0
	global_load_dword v108, v166, s[100:101] nt
	s_add_u32 s100, s100, 0x7e000
	s_addc_u32 s101, s101, 0
	global_load_dword v109, v166, s[100:101] nt
	s_add_u32 s100, s100, 0x7e000
	s_addc_u32 s101, s101, 0
	global_load_dword v110, v166, s[100:101] nt
	s_add_u32 s100, s100, 0x7e000
	s_addc_u32 s101, s101, 0
	global_load_dword v111, v166, s[100:101] nt
	s_add_u32 s100, s100, 0x7e000
	s_addc_u32 s101, s101, 0
	global_load_dword v112, v166, s[100:101] nt
	s_add_u32 s100, s100, 0x7e000
	s_addc_u32 s101, s101, 0
	global_load_dword v113, v166, s[100:101] nt
	s_add_u32 s100, s100, 0x7e000
	s_addc_u32 s101, s101, 0
	global_load_dword v114, v166, s[100:101] nt
	s_add_u32 s100, s100, 0x7e000
	s_addc_u32 s101, s101, 0
	global_load_dword v115, v166, s[100:101] nt
	s_add_u32 s100, s100, 0x7e000
	s_addc_u32 s101, s101, 0
	global_load_dword v116, v166, s[100:101] nt
	s_add_u32 s100, s100, 0x7e000
	s_addc_u32 s101, s101, 0
	global_load_dword v117, v166, s[100:101] nt
	s_add_u32 s100, s100, 0x7e000
	s_addc_u32 s101, s101, 0
	global_load_dword v118, v166, s[100:101] nt
	s_add_u32 s100, s100, 0x7e000
	s_addc_u32 s101, s101, 0
	global_load_dword v119, v166, s[100:101] nt
	s_add_u32 s100, s100, 0x7e000
	s_addc_u32 s101, s101, 0
	global_load_dword v120, v166, s[100:101] nt
	s_add_u32 s100, s100, 0x7e000
	s_addc_u32 s101, s101, 0
	global_load_dword v121, v166, s[100:101] nt
	s_add_u32 s100, s100, 0x7e000
	s_addc_u32 s101, s101, 0
	global_load_dword v122, v166, s[100:101] nt
	s_add_u32 s100, s100, 0x7e000
	s_addc_u32 s101, s101, 0
	global_load_dword v123, v166, s[100:101] nt
	s_add_u32 s100, s100, 0x7e000
	s_addc_u32 s101, s101, 0
	global_load_dword v124, v166, s[100:101] nt
	s_add_u32 s100, s100, 0x7e000
	s_addc_u32 s101, s101, 0
	global_load_dword v125, v166, s[100:101] nt
	s_add_u32 s100, s100, 0x7e000
	s_addc_u32 s101, s101, 0
	global_load_dword v126, v166, s[100:101] nt
	s_add_u32 s100, s100, 0x7e000
	s_addc_u32 s101, s101, 0
	global_load_dword v127, v166, s[100:101] nt
	s_add_u32 s100, s100, 0x7e000
	s_addc_u32 s101, s101, 0
	global_load_dword v128, v166, s[100:101] nt
	s_add_u32 s100, s100, 0x7e000
	s_addc_u32 s101, s101, 0
	global_load_dword v129, v166, s[100:101] nt
	s_add_u32 s100, s100, 0x7e000
	s_addc_u32 s101, s101, 0
	global_load_dword v130, v166, s[100:101] nt
	s_add_u32 s100, s100, 0x7e000
	s_addc_u32 s101, s101, 0
	global_load_dword v131, v166, s[100:101] nt
	s_add_u32 s100, s100, 0x7e000
	s_addc_u32 s101, s101, 0
	global_load_dword v132, v166, s[100:101] nt
	s_add_u32 s100, s100, 0x7e000
	s_addc_u32 s101, s101, 0
	global_load_dword v133, v166, s[100:101] nt
	s_add_u32 s100, s100, 0x7e000
	s_addc_u32 s101, s101, 0
	global_load_dword v134, v166, s[100:101] nt
	s_add_u32 s100, s100, 0x7e000
	s_addc_u32 s101, s101, 0
	global_load_dword v135, v166, s[100:101] nt
	s_add_u32 s100, s100, 0x7e000
	s_addc_u32 s101, s101, 0
	global_load_dword v136, v166, s[100:101] nt
	s_add_u32 s100, s100, 0x7e000
	s_addc_u32 s101, s101, 0
	global_load_dword v137, v166, s[100:101] nt
	s_add_u32 s100, s100, 0x7e000
	s_addc_u32 s101, s101, 0
	global_load_dword v138, v166, s[100:101] nt
	s_add_u32 s100, s100, 0x7e000
	s_addc_u32 s101, s101, 0
	global_load_dword v139, v166, s[100:101] nt
	s_add_u32 s100, s100, 0x7e000
	s_addc_u32 s101, s101, 0
	global_load_dword v140, v166, s[100:101] nt
	s_add_u32 s100, s100, 0x7e000
	s_addc_u32 s101, s101, 0
	global_load_dword v141, v166, s[100:101] nt
	s_add_u32 s100, s100, 0x7e000
	s_addc_u32 s101, s101, 0
	global_load_dword v142, v166, s[100:101] nt
	s_add_u32 s100, s100, 0x7e000
	s_addc_u32 s101, s101, 0
	global_load_dword v143, v166, s[100:101] nt
	s_add_u32 s100, s100, 0x7e000
	s_addc_u32 s101, s101, 0
	global_load_dword v144, v166, s[100:101] nt
	s_add_u32 s100, s100, 0x7e000
	s_addc_u32 s101, s101, 0
	global_load_dword v145, v166, s[100:101] nt
	s_add_u32 s100, s100, 0x7e000
	s_addc_u32 s101, s101, 0
	global_load_dword v146, v166, s[100:101] nt
	s_add_u32 s100, s100, 0x7e000
	s_addc_u32 s101, s101, 0
	global_load_dword v147, v166, s[100:101] nt
	s_add_u32 s100, s100, 0x7e000
	s_addc_u32 s101, s101, 0
	v_cmp_gt_u32_e32 vcc, 16, v150
	s_and_saveexec_b64 s[4:5], vcc
	s_cbranch_execz .Lp0h_skip
	global_load_dword v148, v166, s[100:101] nt

.Lp0b_c1path:
	s_waitcnt lgkmcnt(0)
	v_mov_b32_e32 v16, s20
	ds_read_b64 v[16:17], v16
	s_cmpk_gt_u32 s61, 0x1a0f
	s_cbranch_scc0 .LBB0_73
	s_and_b32 s6, s14, 0xe0
	s_waitcnt lgkmcnt(0)
	v_readfirstlane_b32 s7, v16
	s_and_b32 s2, s16, 0x7c0
	s_lshl_b32 s10, s6, 2
	v_readfirstlane_b32 s11, v17
	s_add_u32 s10, s7, s10
	s_addc_u32 s11, s11, 0
	v_or_b32_e32 v34, s2, v18
	v_lshl_add_u64 v[32:33], s[10:11], 0, v[2:3]
	v_lshl_add_u64 v[32:33], v[32:33], 0, s[4:5]
	v_lshlrev_b32_e32 v34, 10, v34
	v_mov_b32_e32 v35, v3
	v_lshl_add_u64 v[36:37], v[32:33], 0, v[34:35]
	v_add_co_u32_e32 v40, vcc, s21, v36
	v_or_b32_e32 v38, 0x1000, v34
	s_nop 0
	v_addc_co_u32_e32 v41, vcc, 0, v37, vcc
	v_add_co_u32_e32 v44, vcc, s24, v36
	v_mov_b32_e32 v39, v3
	s_nop 0
	v_addc_co_u32_e32 v45, vcc, 0, v37, vcc
	v_add_co_u32_e32 v48, vcc, s25, v36
	v_or_b32_e32 v42, 0x2000, v34
	v_mov_b32_e32 v43, v3
	v_or_b32_e32 v46, 0x3000, v34
	v_mov_b32_e32 v47, v3
	v_addc_co_u32_e32 v49, vcc, 0, v37, vcc
	v_lshl_add_u64 v[38:39], v[32:33], 0, v[38:39]
	v_lshl_add_u64 v[42:43], v[32:33], 0, v[42:43]
	v_lshl_add_u64 v[46:47], v[32:33], 0, v[46:47]
	global_load_dword v54, v[36:37], off nt
	global_load_dword v55, v[36:37], off offset:2048 nt
	global_load_dword v56, v[38:39], off nt
	global_load_dword v57, v[40:41], off offset:2048 nt
	global_load_dword v58, v[42:43], off nt
	global_load_dword v59, v[44:45], off offset:2048 nt
	global_load_dword v60, v[46:47], off nt
	global_load_dword v61, v[48:49], off offset:2048 nt
	v_add_co_u32_e32 v40, vcc, s26, v36
	v_or_b32_e32 v38, 0x4000, v34
	s_nop 0
	v_addc_co_u32_e32 v41, vcc, 0, v37, vcc
	v_add_co_u32_e32 v44, vcc, s27, v36
	v_mov_b32_e32 v39, v3
	s_nop 0
	v_addc_co_u32_e32 v45, vcc, 0, v37, vcc
	v_add_co_u32_e32 v48, vcc, s28, v36
	v_lshl_add_u64 v[38:39], v[32:33], 0, v[38:39]
	s_nop 0
	v_addc_co_u32_e32 v49, vcc, 0, v37, vcc
	v_add_co_u32_e32 v52, vcc, s29, v36
	v_or_b32_e32 v42, 0x5000, v34
	v_mov_b32_e32 v43, v3
	v_or_b32_e32 v46, 0x6000, v34
	v_mov_b32_e32 v47, v3
	v_or_b32_e32 v50, 0x7000, v34
	v_mov_b32_e32 v51, v3
	v_addc_co_u32_e32 v53, vcc, 0, v37, vcc
	v_lshl_add_u64 v[42:43], v[32:33], 0, v[42:43]
	v_lshl_add_u64 v[46:47], v[32:33], 0, v[46:47]
	v_lshl_add_u64 v[50:51], v[32:33], 0, v[50:51]
	global_load_dword v62, v[38:39], off nt
	global_load_dword v63, v[40:41], off offset:2048 nt
	global_load_dword v64, v[42:43], off nt
	global_load_dword v65, v[44:45], off offset:2048 nt
	global_load_dword v66, v[46:47], off nt
	global_load_dword v67, v[48:49], off offset:2048 nt
	global_load_dword v68, v[50:51], off nt
	global_load_dword v69, v[52:53], off offset:2048 nt
	v_add_co_u32_e32 v40, vcc, s30, v36
	v_or_b32_e32 v38, 0x8000, v34
	s_nop 0
	v_addc_co_u32_e32 v41, vcc, 0, v37, vcc
	v_add_co_u32_e32 v44, vcc, s31, v36
	v_mov_b32_e32 v39, v3
	s_nop 0
	v_addc_co_u32_e32 v45, vcc, 0, v37, vcc
	v_add_co_u32_e32 v48, vcc, s33, v36
	v_or_b32_e32 v50, 0xb000, v34
	s_nop 0
	v_addc_co_u32_e32 v49, vcc, 0, v37, vcc
	v_mov_b32_e32 v51, v3
	v_add_co_u32_e32 v52, vcc, s34, v36
	v_lshl_add_u64 v[38:39], v[32:33], 0, v[38:39]
	v_or_b32_e32 v42, 0x9000, v34
	v_mov_b32_e32 v43, v3
	v_or_b32_e32 v46, 0xa000, v34
	v_mov_b32_e32 v47, v3
	v_lshl_add_u64 v[50:51], v[32:33], 0, v[50:51]
	v_addc_co_u32_e32 v53, vcc, 0, v37, vcc
	v_lshl_add_u64 v[42:43], v[32:33], 0, v[42:43]
	v_lshl_add_u64 v[46:47], v[32:33], 0, v[46:47]
	global_load_dword v70, v[38:39], off nt
	global_load_dword v71, v[40:41], off offset:2048 nt
	global_load_dword v72, v[42:43], off nt
	global_load_dword v73, v[44:45], off offset:2048 nt
	global_load_dword v74, v[46:47], off nt
	global_load_dword v75, v[48:49], off offset:2048 nt
	s_nop 0
	global_load_dword v50, v[50:51], off nt
	s_nop 0
	global_load_dword v51, v[52:53], off offset:2048 nt
	v_add_co_u32_e32 v40, vcc, s35, v36
	v_or_b32_e32 v38, 0xc000, v34
	s_nop 0
	v_addc_co_u32_e32 v41, vcc, 0, v37, vcc
	v_add_co_u32_e32 v44, vcc, s36, v36
	v_mov_b32_e32 v39, v3
	s_nop 0
	v_addc_co_u32_e32 v45, vcc, 0, v37, vcc
	v_add_co_u32_e32 v48, vcc, s37, v36
	v_or_b32_e32 v42, 0xd000, v34
	v_mov_b32_e32 v43, v3
	v_or_b32_e32 v46, 0xe000, v34
	v_mov_b32_e32 v47, v3
	v_addc_co_u32_e32 v49, vcc, 0, v37, vcc
	v_or_b32_e32 v34, 0xf000, v34
	v_lshl_add_u64 v[38:39], v[32:33], 0, v[38:39]
	v_lshl_add_u64 v[42:43], v[32:33], 0, v[42:43]
	v_lshl_add_u64 v[46:47], v[32:33], 0, v[46:47]
	v_lshl_add_u64 v[32:33], v[32:33], 0, v[34:35]
	v_add_co_u32_e32 v34, vcc, s38, v36
	s_lshl_b32 s2, s2, 1
	s_nop 0
	v_addc_co_u32_e32 v35, vcc, 0, v37, vcc
	global_load_dword v36, v[38:39], off nt
	global_load_dword v37, v[40:41], off offset:2048 nt
	s_nop 0
	global_load_dword v38, v[42:43], off nt
	global_load_dword v39, v[44:45], off offset:2048 nt
	global_load_dword v40, v[46:47], off nt
	global_load_dword v41, v[48:49], off offset:2048 nt
	s_nop 0
	global_load_dword v32, v[32:33], off nt
	s_nop 0
	global_load_dword v33, v[34:35], off offset:2048 nt
	s_waitcnt vmcnt(0)
	ds_write2_b32 v19, v54, v55 offset1:66
	ds_write2_b32 v19, v56, v57 offset0:132 offset1:198
	ds_write2_b32 v25, v58, v59 offset0:8 offset1:74
	ds_write2_b32 v25, v60, v61 offset0:140 offset1:206
	ds_write2_b32 v26, v62, v63 offset0:16 offset1:82
	ds_write2_b32 v26, v64, v65 offset0:148 offset1:214
	ds_write2_b32 v27, v66, v67 offset0:24 offset1:90
	ds_write2_b32 v27, v68, v69 offset0:156 offset1:222
	ds_write2_b32 v28, v70, v71 offset0:32 offset1:98
	ds_write2_b32 v28, v72, v73 offset0:164 offset1:230
	ds_write2_b32 v29, v74, v75 offset0:40 offset1:106
	ds_write2_b32 v29, v50, v51 offset0:172 offset1:238
	ds_write2_b32 v30, v36, v37 offset0:48 offset1:114
	ds_write2_b32 v30, v38, v39 offset0:180 offset1:246
	ds_write2_b32 v31, v40, v41 offset0:56 offset1:122
	ds_write2_b32 v31, v32, v33 offset0:188 offset1:254
	s_waitcnt lgkmcnt(0)
	ds_read2_b32 v[36:37], v21 offset1:8
	ds_read2_b32 v[40:41], v21 offset0:33 offset1:41
	ds_read2_b32 v[42:43], v21 offset0:66 offset1:74
	ds_read2_b32 v[44:45], v21 offset0:99 offset1:107
	ds_read2_b32 v[46:47], v21 offset0:132 offset1:140
	s_waitcnt lgkmcnt(4)
	v_bfe_u32 v32, v36, 16, 1
	v_add3_u32 v32, v36, v32, s39
	s_waitcnt lgkmcnt(3)
	v_bfe_u32 v33, v40, 16, 1
	v_lshrrev_b32_e32 v32, 16, v32
	v_add3_u32 v33, v40, v33, s39
	ds_read2_b32 v[48:49], v21 offset0:165 offset1:173
	v_and_or_b32 v32, v33, s40, v32
	s_waitcnt lgkmcnt(3)
	v_bfe_u32 v33, v42, 16, 1
	v_add3_u32 v33, v42, v33, s39
	s_waitcnt lgkmcnt(2)
	v_bfe_u32 v34, v44, 16, 1
	ds_read2_b32 v[50:51], v21 offset0:198 offset1:206
	v_lshrrev_b32_e32 v33, 16, v33
	v_add3_u32 v34, v44, v34, s39
	ds_read2_b32 v[52:53], v21 offset0:231 offset1:239
	v_and_or_b32 v33, v34, s40, v33
	s_waitcnt lgkmcnt(3)
	v_bfe_u32 v34, v46, 16, 1
	v_add3_u32 v34, v46, v34, s39
	s_waitcnt lgkmcnt(2)
	v_bfe_u32 v35, v48, 16, 1
	v_lshrrev_b32_e32 v34, 16, v34
	v_add3_u32 v35, v48, v35, s39
	v_and_or_b32 v34, v35, s40, v34
	s_waitcnt lgkmcnt(1)
	v_bfe_u32 v35, v50, 16, 1
	v_add3_u32 v35, v50, v35, s39
	s_waitcnt lgkmcnt(0)
	v_bfe_u32 v36, v52, 16, 1
	v_lshrrev_b32_e32 v35, 16, v35
	v_add3_u32 v36, v52, v36, s39
	v_and_or_b32 v35, v36, s40, v35
	v_or_b32_e32 v36, s6, v20
	v_lshl_add_u64 v[38:39], v[6:7], 0, s[2:3]
	v_lshlrev_b32_e32 v54, 12, v36
	v_mov_b32_e32 v55, v3
	v_lshl_add_u64 v[54:55], v[38:39], 0, v[54:55]
	global_store_dwordx4 v[54:55], v[32:35], off
	v_bfe_u32 v36, v53, 16, 1
	v_add3_u32 v36, v53, v36, s39
	v_bfe_u32 v32, v37, 16, 1
	v_add3_u32 v32, v37, v32, s39
	v_bfe_u32 v33, v41, 16, 1
	v_lshrrev_b32_e32 v32, 16, v32
	v_add3_u32 v33, v41, v33, s39
	v_and_or_b32 v32, v33, s40, v32
	v_bfe_u32 v33, v43, 16, 1
	v_add3_u32 v33, v43, v33, s39
	v_bfe_u32 v34, v45, 16, 1
	v_lshrrev_b32_e32 v33, 16, v33
	v_add3_u32 v34, v45, v34, s39
	v_and_or_b32 v33, v34, s40, v33
	v_bfe_u32 v34, v47, 16, 1
	v_add3_u32 v34, v47, v34, s39
	v_bfe_u32 v35, v49, 16, 1
	v_lshrrev_b32_e32 v34, 16, v34
	v_add3_u32 v35, v49, v35, s39
	v_and_or_b32 v34, v35, s40, v34
	v_bfe_u32 v35, v51, 16, 1
	v_add3_u32 v35, v51, v35, s39
	v_lshrrev_b32_e32 v35, 16, v35
	v_and_or_b32 v35, v36, s40, v35
	v_or_b32_e32 v36, s6, v22
	v_lshlrev_b32_e32 v36, 12, v36
	v_mov_b32_e32 v37, v3
	ds_read2_b32 v[40:41], v21 offset0:16 offset1:24
	v_lshl_add_u64 v[36:37], v[38:39], 0, v[36:37]
	global_store_dwordx4 v[36:37], v[32:35], off
	ds_read2_b32 v[36:37], v21 offset0:49 offset1:57
	ds_read2_b32 v[42:43], v21 offset0:82 offset1:90
	ds_read2_b32 v[44:45], v21 offset0:115 offset1:123
	s_waitcnt lgkmcnt(3)
	v_bfe_u32 v32, v40, 16, 1
	v_add3_u32 v32, v40, v32, s39
	s_waitcnt lgkmcnt(2)
	v_bfe_u32 v33, v36, 16, 1
	ds_read2_b32 v[46:47], v21 offset0:148 offset1:156
	v_lshrrev_b32_e32 v32, 16, v32
	v_add3_u32 v33, v36, v33, s39
	ds_read2_b32 v[48:49], v21 offset0:181 offset1:189
	v_and_or_b32 v32, v33, s40, v32
	s_waitcnt lgkmcnt(3)
	v_bfe_u32 v33, v42, 16, 1
	v_add3_u32 v33, v42, v33, s39
	s_waitcnt lgkmcnt(2)
	v_bfe_u32 v34, v44, 16, 1
	ds_read2_b32 v[50:51], v21 offset0:214 offset1:222
	v_lshrrev_b32_e32 v33, 16, v33
	v_add3_u32 v34, v44, v34, s39
	ds_read2_b32 v[52:53], v21 offset0:247 offset1:255
	v_and_or_b32 v33, v34, s40, v33
	s_waitcnt lgkmcnt(3)
	v_bfe_u32 v34, v46, 16, 1
	v_add3_u32 v34, v46, v34, s39
	s_waitcnt lgkmcnt(2)
	v_bfe_u32 v35, v48, 16, 1
	v_lshrrev_b32_e32 v34, 16, v34
	v_add3_u32 v35, v48, v35, s39
	v_and_or_b32 v34, v35, s40, v34
	s_waitcnt lgkmcnt(1)
	v_bfe_u32 v35, v50, 16, 1
	v_add3_u32 v35, v50, v35, s39
	s_waitcnt lgkmcnt(0)
	v_bfe_u32 v36, v52, 16, 1
	v_lshrrev_b32_e32 v35, 16, v35
	v_add3_u32 v36, v52, v36, s39
	v_and_or_b32 v35, v36, s40, v35
	v_or_b32_e32 v36, s6, v23
	v_lshlrev_b32_e32 v54, 12, v36
	v_mov_b32_e32 v55, v3
	v_lshl_add_u64 v[54:55], v[38:39], 0, v[54:55]
	global_store_dwordx4 v[54:55], v[32:35], off
	v_bfe_u32 v36, v53, 16, 1
	v_add3_u32 v36, v53, v36, s39
	v_bfe_u32 v32, v41, 16, 1
	v_add3_u32 v32, v41, v32, s39
	v_bfe_u32 v33, v37, 16, 1
	v_lshrrev_b32_e32 v32, 16, v32
	v_add3_u32 v33, v37, v33, s39
	v_and_or_b32 v32, v33, s40, v32
	v_bfe_u32 v33, v43, 16, 1
	v_add3_u32 v33, v43, v33, s39
	v_bfe_u32 v34, v45, 16, 1
	v_lshrrev_b32_e32 v33, 16, v33
	v_add3_u32 v34, v45, v34, s39
	v_and_or_b32 v33, v34, s40, v33
	v_bfe_u32 v34, v47, 16, 1
	v_add3_u32 v34, v47, v34, s39
	v_bfe_u32 v35, v49, 16, 1
	v_lshrrev_b32_e32 v34, 16, v34
	v_add3_u32 v35, v49, v35, s39
	v_and_or_b32 v34, v35, s40, v34
	v_bfe_u32 v35, v51, 16, 1
	v_add3_u32 v35, v51, v35, s39
	v_lshrrev_b32_e32 v35, 16, v35
	v_and_or_b32 v35, v36, s40, v35
	v_add_lshl_u32 v36, s6, v24, 12
	v_mov_b32_e32 v37, v3
	v_lshl_add_u64 v[36:37], v[38:39], 0, v[36:37]
	global_store_dwordx4 v[36:37], v[32:35], off
	s_waitcnt lgkmcnt(0)
	s_mov_b64 s[6:7], 0
.LBB0_73:
	s_andn2_b64 vcc, exec, s[6:7]
	s_cbranch_vccnz .LBB0_75
	s_and_b32 s6, s14, 0xe0
	s_waitcnt lgkmcnt(0)
	v_readfirstlane_b32 s7, v16
	s_and_b32 s2, s16, 0x7c0
	s_lshl_b32 s10, s6, 2
	v_readfirstlane_b32 s11, v17
	s_add_u32 s10, s7, s10
	v_or_b32_e32 v32, s2, v18
	s_addc_u32 s11, s11, 0
	v_lshl_add_u64 v[16:17], s[10:11], 0, v[2:3]
	v_lshlrev_b32_e32 v32, 10, v32
	v_mov_b32_e32 v33, v3
	v_lshl_add_u64 v[34:35], v[16:17], 0, v[32:33]
	v_add_co_u32_e32 v38, vcc, s21, v34
	v_or_b32_e32 v36, 0x1000, v32
	s_nop 0
	v_addc_co_u32_e32 v39, vcc, 0, v35, vcc
	v_add_co_u32_e32 v42, vcc, s24, v34
	v_mov_b32_e32 v37, v3
	s_nop 0
	v_addc_co_u32_e32 v43, vcc, 0, v35, vcc
	v_add_co_u32_e32 v46, vcc, s25, v34
	v_or_b32_e32 v40, 0x2000, v32
	v_mov_b32_e32 v41, v3
	v_or_b32_e32 v44, 0x3000, v32
	v_mov_b32_e32 v45, v3
	v_addc_co_u32_e32 v47, vcc, 0, v35, vcc
	v_lshl_add_u64 v[36:37], v[16:17], 0, v[36:37]
	v_lshl_add_u64 v[40:41], v[16:17], 0, v[40:41]
	v_lshl_add_u64 v[44:45], v[16:17], 0, v[44:45]
	global_load_dword v52, v[34:35], off nt
	global_load_dword v53, v[34:35], off offset:2048 nt
	global_load_dword v54, v[36:37], off nt
	global_load_dword v55, v[38:39], off offset:2048 nt
	global_load_dword v56, v[40:41], off nt
	global_load_dword v57, v[42:43], off offset:2048 nt
	global_load_dword v58, v[44:45], off nt
	global_load_dword v59, v[46:47], off offset:2048 nt
	v_add_co_u32_e32 v38, vcc, s26, v34
	v_or_b32_e32 v36, 0x4000, v32
	s_nop 0
	v_addc_co_u32_e32 v39, vcc, 0, v35, vcc
	v_add_co_u32_e32 v42, vcc, s27, v34
	v_mov_b32_e32 v37, v3
	s_nop 0
	v_addc_co_u32_e32 v43, vcc, 0, v35, vcc
	v_add_co_u32_e32 v46, vcc, s28, v34
	v_lshl_add_u64 v[36:37], v[16:17], 0, v[36:37]
	s_nop 0
	v_addc_co_u32_e32 v47, vcc, 0, v35, vcc
	v_add_co_u32_e32 v50, vcc, s29, v34
	v_or_b32_e32 v40, 0x5000, v32
	v_mov_b32_e32 v41, v3
	v_or_b32_e32 v44, 0x6000, v32
	v_mov_b32_e32 v45, v3
	v_or_b32_e32 v48, 0x7000, v32
	v_mov_b32_e32 v49, v3
	v_addc_co_u32_e32 v51, vcc, 0, v35, vcc
	v_lshl_add_u64 v[40:41], v[16:17], 0, v[40:41]
	v_lshl_add_u64 v[44:45], v[16:17], 0, v[44:45]
	v_lshl_add_u64 v[48:49], v[16:17], 0, v[48:49]
	global_load_dword v60, v[36:37], off nt
	global_load_dword v61, v[38:39], off offset:2048 nt
	global_load_dword v62, v[40:41], off nt
	global_load_dword v63, v[42:43], off offset:2048 nt
	global_load_dword v64, v[44:45], off nt
	global_load_dword v65, v[46:47], off offset:2048 nt
	global_load_dword v66, v[48:49], off nt
	global_load_dword v67, v[50:51], off offset:2048 nt
	v_add_co_u32_e32 v38, vcc, s30, v34
	v_or_b32_e32 v36, 0x8000, v32
	s_nop 0
	v_addc_co_u32_e32 v39, vcc, 0, v35, vcc
	v_add_co_u32_e32 v42, vcc, s31, v34
	v_mov_b32_e32 v37, v3
	s_nop 0
	v_addc_co_u32_e32 v43, vcc, 0, v35, vcc
	v_add_co_u32_e32 v46, vcc, s33, v34
	v_or_b32_e32 v48, 0xb000, v32
	s_nop 0
	v_addc_co_u32_e32 v47, vcc, 0, v35, vcc
	v_mov_b32_e32 v49, v3
	v_add_co_u32_e32 v50, vcc, s34, v34
	v_lshl_add_u64 v[36:37], v[16:17], 0, v[36:37]
	v_or_b32_e32 v40, 0x9000, v32
	v_mov_b32_e32 v41, v3
	v_or_b32_e32 v44, 0xa000, v32
	v_mov_b32_e32 v45, v3
	v_lshl_add_u64 v[48:49], v[16:17], 0, v[48:49]
	v_addc_co_u32_e32 v51, vcc, 0, v35, vcc
	v_lshl_add_u64 v[40:41], v[16:17], 0, v[40:41]
	v_lshl_add_u64 v[44:45], v[16:17], 0, v[44:45]
	global_load_dword v68, v[36:37], off nt
	global_load_dword v69, v[38:39], off offset:2048 nt
	global_load_dword v70, v[40:41], off nt
	global_load_dword v71, v[42:43], off offset:2048 nt
	global_load_dword v72, v[44:45], off nt
	global_load_dword v73, v[46:47], off offset:2048 nt
	s_nop 0
	global_load_dword v48, v[48:49], off nt
	s_nop 0
	global_load_dword v49, v[50:51], off offset:2048 nt
	v_add_co_u32_e32 v38, vcc, s35, v34
	v_or_b32_e32 v36, 0xc000, v32
	s_nop 0
	v_addc_co_u32_e32 v39, vcc, 0, v35, vcc
	v_add_co_u32_e32 v42, vcc, s36, v34
	v_mov_b32_e32 v37, v3
	s_nop 0
	v_addc_co_u32_e32 v43, vcc, 0, v35, vcc
	v_add_co_u32_e32 v46, vcc, s37, v34
	v_or_b32_e32 v40, 0xd000, v32
	v_mov_b32_e32 v41, v3
	v_or_b32_e32 v44, 0xe000, v32
	v_mov_b32_e32 v45, v3
	v_addc_co_u32_e32 v47, vcc, 0, v35, vcc
	v_or_b32_e32 v32, 0xf000, v32
	v_lshl_add_u64 v[36:37], v[16:17], 0, v[36:37]
	v_lshl_add_u64 v[40:41], v[16:17], 0, v[40:41]
	v_lshl_add_u64 v[44:45], v[16:17], 0, v[44:45]
	v_lshl_add_u64 v[16:17], v[16:17], 0, v[32:33]
	v_add_co_u32_e32 v32, vcc, s38, v34
	s_lshl_b32 s2, s2, 1
	s_nop 0
	v_addc_co_u32_e32 v33, vcc, 0, v35, vcc
	global_load_dword v34, v[36:37], off nt
	global_load_dword v35, v[38:39], off offset:2048 nt
	s_nop 0
	global_load_dword v36, v[40:41], off nt
	global_load_dword v37, v[42:43], off offset:2048 nt
	global_load_dword v38, v[44:45], off nt
	global_load_dword v39, v[46:47], off offset:2048 nt
	s_nop 0
	global_load_dword v16, v[16:17], off nt
	s_nop 0
	global_load_dword v17, v[32:33], off offset:2048 nt
	s_waitcnt vmcnt(0)
	ds_write2_b32 v19, v52, v53 offset1:66
	ds_write2_b32 v19, v54, v55 offset0:132 offset1:198
	ds_write2_b32 v25, v56, v57 offset0:8 offset1:74
	ds_write2_b32 v25, v58, v59 offset0:140 offset1:206
	ds_write2_b32 v26, v60, v61 offset0:16 offset1:82
	ds_write2_b32 v26, v62, v63 offset0:148 offset1:214
	ds_write2_b32 v27, v64, v65 offset0:24 offset1:90
	ds_write2_b32 v27, v66, v67 offset0:156 offset1:222
	ds_write2_b32 v28, v68, v69 offset0:32 offset1:98
	ds_write2_b32 v28, v70, v71 offset0:164 offset1:230
	ds_write2_b32 v29, v72, v73 offset0:40 offset1:106
	ds_write2_b32 v29, v48, v49 offset0:172 offset1:238
	ds_write2_b32 v30, v34, v35 offset0:48 offset1:114
	ds_write2_b32 v30, v36, v37 offset0:180 offset1:246
	ds_write2_b32 v31, v38, v39 offset0:56 offset1:122
	ds_write2_b32 v31, v16, v17 offset0:188 offset1:254
	s_waitcnt lgkmcnt(0)
	ds_read2_b32 v[16:17], v21 offset1:8
	ds_read2_b32 v[38:39], v21 offset0:33 offset1:41
	ds_read2_b32 v[40:41], v21 offset0:66 offset1:74
	ds_read2_b32 v[42:43], v21 offset0:99 offset1:107
	ds_read2_b32 v[44:45], v21 offset0:132 offset1:140
	s_waitcnt lgkmcnt(4)
	v_bfe_u32 v32, v16, 16, 1
	v_add3_u32 v16, v16, v32, s39
	s_waitcnt lgkmcnt(3)
	v_bfe_u32 v32, v38, 16, 1
	v_lshrrev_b32_e32 v16, 16, v16
	v_add3_u32 v32, v38, v32, s39
	ds_read2_b32 v[46:47], v21 offset0:165 offset1:173
	v_and_or_b32 v32, v32, s40, v16
	s_waitcnt lgkmcnt(3)
	v_bfe_u32 v16, v40, 16, 1
	v_add3_u32 v16, v40, v16, s39
	s_waitcnt lgkmcnt(2)
	v_bfe_u32 v33, v42, 16, 1
	ds_read2_b32 v[48:49], v21 offset0:198 offset1:206
	v_lshrrev_b32_e32 v16, 16, v16
	v_add3_u32 v33, v42, v33, s39
	ds_read2_b32 v[50:51], v21 offset0:231 offset1:239
	v_and_or_b32 v33, v33, s40, v16
	s_waitcnt lgkmcnt(3)
	v_bfe_u32 v16, v44, 16, 1
	v_add3_u32 v16, v44, v16, s39
	s_waitcnt lgkmcnt(2)
	v_bfe_u32 v34, v46, 16, 1
	v_lshrrev_b32_e32 v16, 16, v16
	v_add3_u32 v34, v46, v34, s39
	v_and_or_b32 v34, v34, s40, v16
	s_waitcnt lgkmcnt(1)
	v_bfe_u32 v16, v48, 16, 1
	v_add3_u32 v16, v48, v16, s39
	s_waitcnt lgkmcnt(0)
	v_bfe_u32 v35, v50, 16, 1
	v_lshrrev_b32_e32 v16, 16, v16
	v_add3_u32 v35, v50, v35, s39
	v_and_or_b32 v35, v35, s40, v16
	v_or_b32_e32 v16, s6, v20
	v_lshlrev_b32_e32 v52, 12, v16
	v_bfe_u32 v16, v17, 16, 1
	v_lshl_add_u64 v[36:37], v[8:9], 0, s[2:3]
	v_mov_b32_e32 v53, v3
	v_add3_u32 v16, v17, v16, s39
	v_bfe_u32 v17, v39, 16, 1
	v_lshl_add_u64 v[52:53], v[36:37], 0, v[52:53]
	v_lshrrev_b32_e32 v16, 16, v16
	v_add3_u32 v17, v39, v17, s39
	global_store_dwordx4 v[52:53], v[32:35], off
	ds_read2_b32 v[38:39], v21 offset0:16 offset1:24
	v_mov_b32_e32 v53, v3
	v_and_or_b32 v32, v17, s40, v16
	v_bfe_u32 v16, v41, 16, 1
	v_add3_u32 v16, v41, v16, s39
	v_bfe_u32 v17, v43, 16, 1
	v_lshrrev_b32_e32 v16, 16, v16
	v_add3_u32 v17, v43, v17, s39
	v_and_or_b32 v33, v17, s40, v16
	v_bfe_u32 v16, v45, 16, 1
	v_add3_u32 v16, v45, v16, s39
	v_bfe_u32 v17, v47, 16, 1
	v_lshrrev_b32_e32 v16, 16, v16
	v_add3_u32 v17, v47, v17, s39
	v_and_or_b32 v34, v17, s40, v16
	v_bfe_u32 v16, v49, 16, 1
	v_add3_u32 v16, v49, v16, s39
	v_bfe_u32 v17, v51, 16, 1
	v_lshrrev_b32_e32 v16, 16, v16
	v_add3_u32 v17, v51, v17, s39
	v_and_or_b32 v35, v17, s40, v16
	v_or_b32_e32 v16, s6, v22
	v_lshlrev_b32_e32 v16, 12, v16
	v_mov_b32_e32 v17, v3
	v_lshl_add_u64 v[16:17], v[36:37], 0, v[16:17]
	global_store_dwordx4 v[16:17], v[32:35], off
	ds_read2_b32 v[16:17], v21 offset0:49 offset1:57
	ds_read2_b32 v[40:41], v21 offset0:82 offset1:90
	ds_read2_b32 v[42:43], v21 offset0:115 offset1:123
	s_waitcnt lgkmcnt(3)
	v_bfe_u32 v32, v38, 16, 1
	v_add3_u32 v32, v38, v32, s39
	s_waitcnt lgkmcnt(2)
	v_bfe_u32 v33, v16, 16, 1
	ds_read2_b32 v[44:45], v21 offset0:148 offset1:156
	v_lshrrev_b32_e32 v32, 16, v32
	v_add3_u32 v16, v16, v33, s39
	ds_read2_b32 v[46:47], v21 offset0:181 offset1:189
	v_and_or_b32 v32, v16, s40, v32
	s_waitcnt lgkmcnt(3)
	v_bfe_u32 v16, v40, 16, 1
	v_add3_u32 v16, v40, v16, s39
	s_waitcnt lgkmcnt(2)
	v_bfe_u32 v33, v42, 16, 1
	ds_read2_b32 v[48:49], v21 offset0:214 offset1:222
	v_lshrrev_b32_e32 v16, 16, v16
	v_add3_u32 v33, v42, v33, s39
	ds_read2_b32 v[50:51], v21 offset0:247 offset1:255
	v_and_or_b32 v33, v33, s40, v16
	s_waitcnt lgkmcnt(3)
	v_bfe_u32 v16, v44, 16, 1
	v_add3_u32 v16, v44, v16, s39
	s_waitcnt lgkmcnt(2)
	v_bfe_u32 v34, v46, 16, 1
	v_lshrrev_b32_e32 v16, 16, v16
	v_add3_u32 v34, v46, v34, s39
	v_and_or_b32 v34, v34, s40, v16
	s_waitcnt lgkmcnt(1)
	v_bfe_u32 v16, v48, 16, 1
	v_add3_u32 v16, v48, v16, s39
	s_waitcnt lgkmcnt(0)
	v_bfe_u32 v35, v50, 16, 1
	v_lshrrev_b32_e32 v16, 16, v16
	v_add3_u32 v35, v50, v35, s39
	v_and_or_b32 v35, v35, s40, v16
	v_or_b32_e32 v16, s6, v23
	v_lshlrev_b32_e32 v52, 12, v16
	v_lshl_add_u64 v[52:53], v[36:37], 0, v[52:53]
	v_bfe_u32 v16, v39, 16, 1
	global_store_dwordx4 v[52:53], v[32:35], off
	v_add3_u32 v16, v39, v16, s39
	v_lshrrev_b32_e32 v16, 16, v16
	v_bfe_u32 v32, v17, 16, 1
	v_add3_u32 v17, v17, v32, s39
	v_and_or_b32 v32, v17, s40, v16
	v_bfe_u32 v16, v41, 16, 1
	v_add3_u32 v16, v41, v16, s39
	v_bfe_u32 v17, v43, 16, 1
	v_lshrrev_b32_e32 v16, 16, v16
	v_add3_u32 v17, v43, v17, s39
	v_and_or_b32 v33, v17, s40, v16
	v_bfe_u32 v16, v45, 16, 1
	v_add3_u32 v16, v45, v16, s39
	v_bfe_u32 v17, v47, 16, 1
	v_lshrrev_b32_e32 v16, 16, v16
	v_add3_u32 v17, v47, v17, s39
	v_and_or_b32 v34, v17, s40, v16
	v_bfe_u32 v16, v49, 16, 1
	v_add3_u32 v16, v49, v16, s39
	v_bfe_u32 v17, v51, 16, 1
	v_lshrrev_b32_e32 v16, 16, v16
	v_add3_u32 v17, v51, v17, s39
	v_and_or_b32 v35, v17, s40, v16
	v_add_lshl_u32 v16, s6, v24, 12
	v_mov_b32_e32 v17, v3
	v_lshl_add_u64 v[16:17], v[36:37], 0, v[16:17]
	global_store_dwordx4 v[16:17], v[32:35], off
	s_waitcnt lgkmcnt(0)

.LBB0_76:
	s_andn2_b64 vcc, exec, s[6:7]
	s_cbranch_vccnz .LBB0_78
	s_waitcnt lgkmcnt(0)
	v_mov_b32_e32 v16, s41
	ds_read_b64 v[16:17], v16
	s_add_i32 s6, s14, 0xfffd8e00
	s_and_b32 s6, s6, 0x3e0
	s_and_b32 s2, s18, 0x1ffc0
	s_lshl_b32 s10, s6, 2
	s_waitcnt lgkmcnt(0)
	v_readfirstlane_b32 s7, v16
	v_readfirstlane_b32 s11, v17
	s_add_u32 s10, s7, s10
	v_or_b32_e32 v32, s2, v18
	s_addc_u32 s11, s11, 0
	v_lshl_add_u64 v[16:17], s[10:11], 0, v[2:3]
	v_lshlrev_b32_e32 v32, 12, v32
	v_mov_b32_e32 v33, v3
	v_lshl_add_u64 v[34:35], v[16:17], 0, v[32:33]
	v_add_co_u32_e32 v36, vcc, s24, v34
	v_or_b32_e32 v38, 0x4000, v32
	s_nop 0
	v_addc_co_u32_e32 v37, vcc, 0, v35, vcc
	v_add_co_u32_e32 v40, vcc, s28, v34
	v_mov_b32_e32 v39, v3
	s_nop 0
	v_addc_co_u32_e32 v41, vcc, 0, v35, vcc
	v_add_co_u32_e32 v44, vcc, s33, v34
	v_lshl_add_u64 v[38:39], v[16:17], 0, v[38:39]
	s_nop 0
	v_addc_co_u32_e32 v45, vcc, 0, v35, vcc
	v_add_co_u32_e32 v48, vcc, s37, v34
	v_or_b32_e32 v42, 0x8000, v32
	v_mov_b32_e32 v43, v3
	v_or_b32_e32 v46, 0xc000, v32
	v_mov_b32_e32 v47, v3
	v_addc_co_u32_e32 v49, vcc, 0, v35, vcc
	v_lshl_add_u64 v[42:43], v[16:17], 0, v[42:43]
	v_lshl_add_u64 v[46:47], v[16:17], 0, v[46:47]
	global_load_dword v52, v[34:35], off nt
	global_load_dword v53, v[36:37], off nt
	global_load_dword v54, v[38:39], off nt
	global_load_dword v55, v[40:41], off nt
	global_load_dword v56, v[42:43], off nt
	global_load_dword v57, v[44:45], off nt
	global_load_dword v58, v[46:47], off nt
	global_load_dword v59, v[48:49], off nt
	v_add_co_u32_e32 v38, vcc, s42, v34
	v_or_b32_e32 v36, 0x10000, v32
	s_nop 0
	v_addc_co_u32_e32 v39, vcc, 0, v35, vcc
	v_add_co_u32_e32 v42, vcc, s43, v34
	v_mov_b32_e32 v37, v3
	s_nop 0
	v_addc_co_u32_e32 v43, vcc, 0, v35, vcc
	v_add_co_u32_e32 v46, vcc, s44, v34
	v_lshl_add_u64 v[36:37], v[16:17], 0, v[36:37]
	s_nop 0
	v_addc_co_u32_e32 v47, vcc, 0, v35, vcc
	v_add_co_u32_e32 v50, vcc, s45, v34
	v_or_b32_e32 v40, 0x14000, v32
	v_mov_b32_e32 v41, v3
	v_or_b32_e32 v44, 0x18000, v32
	v_mov_b32_e32 v45, v3
	v_or_b32_e32 v48, 0x1c000, v32
	v_mov_b32_e32 v49, v3
	v_addc_co_u32_e32 v51, vcc, 0, v35, vcc
	v_lshl_add_u64 v[40:41], v[16:17], 0, v[40:41]
	v_lshl_add_u64 v[44:45], v[16:17], 0, v[44:45]
	v_lshl_add_u64 v[48:49], v[16:17], 0, v[48:49]
	global_load_dword v60, v[36:37], off nt
	global_load_dword v61, v[38:39], off nt
	global_load_dword v62, v[40:41], off nt
	global_load_dword v63, v[42:43], off nt
	global_load_dword v64, v[44:45], off nt
	global_load_dword v65, v[46:47], off nt
	global_load_dword v66, v[48:49], off nt
	global_load_dword v67, v[50:51], off nt
	v_add_co_u32_e32 v38, vcc, s46, v34
	v_or_b32_e32 v36, 0x20000, v32
	s_nop 0
	v_addc_co_u32_e32 v39, vcc, 0, v35, vcc
	v_add_co_u32_e32 v42, vcc, s47, v34
	v_mov_b32_e32 v37, v3
	s_nop 0
	v_addc_co_u32_e32 v43, vcc, 0, v35, vcc
	v_add_co_u32_e32 v46, vcc, s48, v34
	v_or_b32_e32 v48, 0x2c000, v32
	s_nop 0
	v_addc_co_u32_e32 v47, vcc, 0, v35, vcc
	v_mov_b32_e32 v49, v3
	v_add_co_u32_e32 v50, vcc, s49, v34
	v_lshl_add_u64 v[36:37], v[16:17], 0, v[36:37]
	v_or_b32_e32 v40, 0x24000, v32
	v_mov_b32_e32 v41, v3
	v_or_b32_e32 v44, 0x28000, v32
	v_mov_b32_e32 v45, v3
	v_lshl_add_u64 v[48:49], v[16:17], 0, v[48:49]
	v_addc_co_u32_e32 v51, vcc, 0, v35, vcc
	v_lshl_add_u64 v[40:41], v[16:17], 0, v[40:41]
	v_lshl_add_u64 v[44:45], v[16:17], 0, v[44:45]
	global_load_dword v68, v[36:37], off nt
	global_load_dword v69, v[38:39], off nt
	global_load_dword v70, v[40:41], off nt
	global_load_dword v71, v[42:43], off nt
	global_load_dword v72, v[44:45], off nt
	global_load_dword v73, v[46:47], off nt
	s_nop 0
	global_load_dword v48, v[48:49], off nt
	s_nop 0
	global_load_dword v49, v[50:51], off nt
	v_add_co_u32_e32 v38, vcc, s50, v34
	v_or_b32_e32 v36, 0x30000, v32
	s_nop 0
	v_addc_co_u32_e32 v39, vcc, 0, v35, vcc
	v_add_co_u32_e32 v42, vcc, s51, v34
	v_mov_b32_e32 v37, v3
	s_nop 0
	v_addc_co_u32_e32 v43, vcc, 0, v35, vcc
	v_add_co_u32_e32 v46, vcc, s52, v34
	v_or_b32_e32 v40, 0x34000, v32
	v_mov_b32_e32 v41, v3
	v_or_b32_e32 v44, 0x38000, v32
	v_mov_b32_e32 v45, v3
	v_addc_co_u32_e32 v47, vcc, 0, v35, vcc
	v_or_b32_e32 v32, 0x3c000, v32
	v_lshl_add_u64 v[36:37], v[16:17], 0, v[36:37]
	v_lshl_add_u64 v[40:41], v[16:17], 0, v[40:41]
	v_lshl_add_u64 v[44:45], v[16:17], 0, v[44:45]
	v_lshl_add_u64 v[16:17], v[16:17], 0, v[32:33]
	v_add_co_u32_e32 v32, vcc, s53, v34
	s_lshl_b32 s2, s2, 1
	s_nop 0
	v_addc_co_u32_e32 v33, vcc, 0, v35, vcc
	global_load_dword v34, v[36:37], off nt
	global_load_dword v35, v[38:39], off nt
	s_nop 0
	global_load_dword v36, v[40:41], off nt
	global_load_dword v37, v[42:43], off nt
	global_load_dword v38, v[44:45], off nt
	global_load_dword v39, v[46:47], off nt
	s_nop 0
	global_load_dword v16, v[16:17], off nt
	s_nop 0
	global_load_dword v17, v[32:33], off nt
	s_waitcnt vmcnt(0)
	ds_write2_b32 v19, v52, v53 offset1:66
	ds_write2_b32 v19, v54, v55 offset0:132 offset1:198
	ds_write2_b32 v25, v56, v57 offset0:8 offset1:74
	ds_write2_b32 v25, v58, v59 offset0:140 offset1:206
	ds_write2_b32 v26, v60, v61 offset0:16 offset1:82
	ds_write2_b32 v26, v62, v63 offset0:148 offset1:214
	ds_write2_b32 v27, v64, v65 offset0:24 offset1:90
	ds_write2_b32 v27, v66, v67 offset0:156 offset1:222
	ds_write2_b32 v28, v68, v69 offset0:32 offset1:98
	ds_write2_b32 v28, v70, v71 offset0:164 offset1:230
	ds_write2_b32 v29, v72, v73 offset0:40 offset1:106
	ds_write2_b32 v29, v48, v49 offset0:172 offset1:238
	ds_write2_b32 v30, v34, v35 offset0:48 offset1:114
	ds_write2_b32 v30, v36, v37 offset0:180 offset1:246
	ds_write2_b32 v31, v38, v39 offset0:56 offset1:122
	ds_write2_b32 v31, v16, v17 offset0:188 offset1:254
	s_waitcnt lgkmcnt(0)
	ds_read2_b32 v[16:17], v21 offset1:8
	ds_read2_b32 v[38:39], v21 offset0:33 offset1:41
	ds_read2_b32 v[40:41], v21 offset0:66 offset1:74
	ds_read2_b32 v[42:43], v21 offset0:99 offset1:107
	ds_read2_b32 v[44:45], v21 offset0:132 offset1:140
	s_waitcnt lgkmcnt(4)
	v_bfe_u32 v32, v16, 16, 1
	v_add3_u32 v16, v16, v32, s39
	s_waitcnt lgkmcnt(3)
	v_bfe_u32 v32, v38, 16, 1
	v_lshrrev_b32_e32 v16, 16, v16
	v_add3_u32 v32, v38, v32, s39
	ds_read2_b32 v[46:47], v21 offset0:165 offset1:173
	v_and_or_b32 v32, v32, s40, v16
	s_waitcnt lgkmcnt(3)
	v_bfe_u32 v16, v40, 16, 1
	v_add3_u32 v16, v40, v16, s39
	s_waitcnt lgkmcnt(2)
	v_bfe_u32 v33, v42, 16, 1
	ds_read2_b32 v[48:49], v21 offset0:198 offset1:206
	v_lshrrev_b32_e32 v16, 16, v16
	v_add3_u32 v33, v42, v33, s39
	ds_read2_b32 v[50:51], v21 offset0:231 offset1:239
	v_and_or_b32 v33, v33, s40, v16
	s_waitcnt lgkmcnt(3)
	v_bfe_u32 v16, v44, 16, 1
	v_add3_u32 v16, v44, v16, s39
	s_waitcnt lgkmcnt(2)
	v_bfe_u32 v34, v46, 16, 1
	v_lshrrev_b32_e32 v16, 16, v16
	v_add3_u32 v34, v46, v34, s39
	v_and_or_b32 v34, v34, s40, v16
	s_waitcnt lgkmcnt(1)
	v_bfe_u32 v16, v48, 16, 1
	v_add3_u32 v16, v48, v16, s39
	s_waitcnt lgkmcnt(0)
	v_bfe_u32 v35, v50, 16, 1
	v_lshrrev_b32_e32 v16, 16, v16
	v_add3_u32 v35, v50, v35, s39
	v_lshl_add_u64 v[36:37], v[10:11], 0, s[2:3]
	v_and_or_b32 v35, v35, s40, v16
	v_or_b32_e32 v16, s6, v20
	v_mad_u64_u32 v[52:53], s[10:11], v16, s54, v[36:37]
	v_bfe_u32 v16, v17, 16, 1
	v_add3_u32 v16, v17, v16, s39
	v_bfe_u32 v17, v39, 16, 1
	v_lshrrev_b32_e32 v16, 16, v16
	v_add3_u32 v17, v39, v17, s39
	global_store_dwordx4 v[52:53], v[32:35], off
	v_or_b32_e32 v38, s6, v22
	v_mad_u64_u32 v[38:39], s[10:11], v38, s54, v[36:37]
	v_and_or_b32 v32, v17, s40, v16
	v_bfe_u32 v16, v41, 16, 1
	v_add3_u32 v16, v41, v16, s39
	v_bfe_u32 v17, v43, 16, 1
	v_lshrrev_b32_e32 v16, 16, v16
	v_add3_u32 v17, v43, v17, s39
	v_and_or_b32 v33, v17, s40, v16
	v_bfe_u32 v16, v45, 16, 1
	v_add3_u32 v16, v45, v16, s39
	v_bfe_u32 v17, v47, 16, 1
	v_lshrrev_b32_e32 v16, 16, v16
	v_add3_u32 v17, v47, v17, s39
	v_and_or_b32 v34, v17, s40, v16
	v_bfe_u32 v16, v49, 16, 1
	v_add3_u32 v16, v49, v16, s39
	v_bfe_u32 v17, v51, 16, 1
	v_lshrrev_b32_e32 v16, 16, v16
	v_add3_u32 v17, v51, v17, s39
	v_and_or_b32 v35, v17, s40, v16
	ds_read2_b32 v[16:17], v21 offset0:16 offset1:24
	global_store_dwordx4 v[38:39], v[32:35], off
	ds_read2_b32 v[38:39], v21 offset0:49 offset1:57
	ds_read2_b32 v[40:41], v21 offset0:82 offset1:90
	ds_read2_b32 v[42:43], v21 offset0:115 offset1:123
	s_waitcnt lgkmcnt(3)
	v_bfe_u32 v32, v16, 16, 1
	v_add3_u32 v16, v16, v32, s39
	s_waitcnt lgkmcnt(2)
	v_bfe_u32 v32, v38, 16, 1
	ds_read2_b32 v[44:45], v21 offset0:148 offset1:156
	v_lshrrev_b32_e32 v16, 16, v16
	v_add3_u32 v32, v38, v32, s39
	ds_read2_b32 v[46:47], v21 offset0:181 offset1:189
	v_and_or_b32 v32, v32, s40, v16
	s_waitcnt lgkmcnt(3)
	v_bfe_u32 v16, v40, 16, 1
	v_add3_u32 v16, v40, v16, s39
	s_waitcnt lgkmcnt(2)
	v_bfe_u32 v33, v42, 16, 1
	ds_read2_b32 v[48:49], v21 offset0:214 offset1:222
	v_lshrrev_b32_e32 v16, 16, v16
	v_add3_u32 v33, v42, v33, s39
	ds_read2_b32 v[50:51], v21 offset0:247 offset1:255
	v_and_or_b32 v33, v33, s40, v16
	s_waitcnt lgkmcnt(3)
	v_bfe_u32 v16, v44, 16, 1
	v_add3_u32 v16, v44, v16, s39
	s_waitcnt lgkmcnt(2)
	v_bfe_u32 v34, v46, 16, 1
	v_lshrrev_b32_e32 v16, 16, v16
	v_add3_u32 v34, v46, v34, s39
	v_and_or_b32 v34, v34, s40, v16
	s_waitcnt lgkmcnt(1)
	v_bfe_u32 v16, v48, 16, 1
	v_add3_u32 v16, v48, v16, s39
	s_waitcnt lgkmcnt(0)
	v_bfe_u32 v35, v50, 16, 1
	v_lshrrev_b32_e32 v16, 16, v16
	v_add3_u32 v35, v50, v35, s39
	v_and_or_b32 v35, v35, s40, v16
	v_or_b32_e32 v16, s6, v23
	v_mad_u64_u32 v[52:53], s[10:11], v16, s54, v[36:37]
	v_bfe_u32 v16, v17, 16, 1
	v_add3_u32 v16, v17, v16, s39
	v_bfe_u32 v17, v39, 16, 1
	v_lshrrev_b32_e32 v16, 16, v16
	v_add3_u32 v17, v39, v17, s39
	global_store_dwordx4 v[52:53], v[32:35], off
	s_nop 1
	v_and_or_b32 v32, v17, s40, v16
	v_bfe_u32 v16, v41, 16, 1
	v_add3_u32 v16, v41, v16, s39
	v_bfe_u32 v17, v43, 16, 1
	v_lshrrev_b32_e32 v16, 16, v16
	v_add3_u32 v17, v43, v17, s39
	v_and_or_b32 v33, v17, s40, v16
	v_bfe_u32 v16, v45, 16, 1
	v_add3_u32 v16, v45, v16, s39
	v_bfe_u32 v17, v47, 16, 1
	v_lshrrev_b32_e32 v16, 16, v16
	v_add3_u32 v17, v47, v17, s39
	v_and_or_b32 v34, v17, s40, v16
	v_bfe_u32 v16, v49, 16, 1
	v_add3_u32 v16, v49, v16, s39
	v_bfe_u32 v17, v51, 16, 1
	v_lshrrev_b32_e32 v16, 16, v16
	v_add3_u32 v17, v51, v17, s39
	v_and_or_b32 v35, v17, s40, v16
	v_add_u32_e32 v16, s6, v24
	v_mad_u64_u32 v[16:17], s[6:7], v16, s54, v[36:37]
	global_store_dwordx4 v[16:17], v[32:35], off
	s_waitcnt lgkmcnt(0)

.LBB0_84:
	s_lshl_b32 s6, s12, 6
	s_and_b32 s12, s6, 0x7fc0
	s_lshl_b32 s6, s13, 2
	s_add_u32 s6, s2, s6
	v_or_b32_e32 v48, s12, v18
	s_addc_u32 s7, s11, 0
	v_lshl_add_u64 v[16:17], s[6:7], 0, v[2:3]
	v_add_u32_e32 v34, 2, v48
	v_or_b32_e32 v36, 4, v48
	v_add_u32_e32 v38, 6, v48
	v_or_b32_e32 v40, 8, v48
	v_add_u32_e32 v42, 10, v48
	v_or_b32_e32 v44, 12, v48
	v_add_u32_e32 v46, 14, v48
	v_mad_u64_u32 v[32:33], s[6:7], v48, s56, v[16:17]
	v_mad_u64_u32 v[34:35], s[6:7], v34, s56, v[16:17]
	v_mad_u64_u32 v[36:37], s[6:7], v36, s56, v[16:17]
	v_mad_u64_u32 v[38:39], s[6:7], v38, s56, v[16:17]
	v_mad_u64_u32 v[40:41], s[6:7], v40, s56, v[16:17]
	v_mad_u64_u32 v[42:43], s[6:7], v42, s56, v[16:17]
	v_mad_u64_u32 v[44:45], s[6:7], v44, s56, v[16:17]
	v_mad_u64_u32 v[46:47], s[6:7], v46, s56, v[16:17]
	global_load_dword v49, v[32:33], off nt
	global_load_dword v50, v[34:35], off nt
	global_load_dword v51, v[36:37], off nt
	global_load_dword v52, v[38:39], off nt
	global_load_dword v53, v[40:41], off nt
	global_load_dword v54, v[42:43], off nt
	global_load_dword v55, v[44:45], off nt
	global_load_dword v56, v[46:47], off nt
	v_or_b32_e32 v32, 16, v48
	v_add_u32_e32 v34, 18, v48
	v_or_b32_e32 v36, 20, v48
	v_add_u32_e32 v38, 22, v48
	v_or_b32_e32 v40, 24, v48
	v_add_u32_e32 v42, 26, v48
	v_or_b32_e32 v44, 28, v48
	v_add_u32_e32 v46, 30, v48
	v_mad_u64_u32 v[32:33], s[6:7], v32, s56, v[16:17]
	v_mad_u64_u32 v[34:35], s[6:7], v34, s56, v[16:17]
	v_mad_u64_u32 v[36:37], s[6:7], v36, s56, v[16:17]
	v_mad_u64_u32 v[38:39], s[6:7], v38, s56, v[16:17]
	v_mad_u64_u32 v[40:41], s[6:7], v40, s56, v[16:17]
	v_mad_u64_u32 v[42:43], s[6:7], v42, s56, v[16:17]
	v_mad_u64_u32 v[44:45], s[6:7], v44, s56, v[16:17]
	v_mad_u64_u32 v[46:47], s[6:7], v46, s56, v[16:17]
	global_load_dword v57, v[32:33], off nt
	global_load_dword v58, v[34:35], off nt
	global_load_dword v59, v[36:37], off nt
	global_load_dword v60, v[38:39], off nt
	global_load_dword v61, v[40:41], off nt
	global_load_dword v62, v[42:43], off nt
	global_load_dword v63, v[44:45], off nt
	global_load_dword v64, v[46:47], off nt
	v_or_b32_e32 v32, 32, v48
	v_add_u32_e32 v34, 34, v48
	v_or_b32_e32 v36, 36, v48
	v_add_u32_e32 v38, 38, v48
	v_or_b32_e32 v40, 40, v48
	v_add_u32_e32 v42, 42, v48
	v_or_b32_e32 v44, 44, v48
	v_add_u32_e32 v46, 46, v48
	v_mad_u64_u32 v[32:33], s[6:7], v32, s56, v[16:17]
	v_mad_u64_u32 v[34:35], s[6:7], v34, s56, v[16:17]
	v_mad_u64_u32 v[36:37], s[6:7], v36, s56, v[16:17]
	v_mad_u64_u32 v[38:39], s[6:7], v38, s56, v[16:17]
	v_mad_u64_u32 v[40:41], s[6:7], v40, s56, v[16:17]
	v_mad_u64_u32 v[42:43], s[6:7], v42, s56, v[16:17]
	v_mad_u64_u32 v[44:45], s[6:7], v44, s56, v[16:17]
	v_mad_u64_u32 v[46:47], s[6:7], v46, s56, v[16:17]
	global_load_dword v65, v[32:33], off nt
	global_load_dword v66, v[34:35], off nt
	global_load_dword v67, v[36:37], off nt
	global_load_dword v68, v[38:39], off nt
	global_load_dword v69, v[40:41], off nt
	global_load_dword v70, v[42:43], off nt
	global_load_dword v71, v[44:45], off nt
	s_nop 0
	global_load_dword v46, v[46:47], off nt
	v_or_b32_e32 v32, 48, v48
	v_add_u32_e32 v34, 50, v48
	v_or_b32_e32 v36, 52, v48
	v_add_u32_e32 v38, 54, v48
	v_or_b32_e32 v40, 56, v48
	v_add_u32_e32 v42, 58, v48
	v_or_b32_e32 v44, 60, v48
	v_add_u32_e32 v47, 62, v48
	v_mad_u64_u32 v[32:33], s[6:7], v32, s56, v[16:17]
	v_mad_u64_u32 v[34:35], s[6:7], v34, s56, v[16:17]
	v_mad_u64_u32 v[36:37], s[6:7], v36, s56, v[16:17]
	v_mad_u64_u32 v[38:39], s[6:7], v38, s56, v[16:17]
	v_mad_u64_u32 v[40:41], s[6:7], v40, s56, v[16:17]
	v_mad_u64_u32 v[42:43], s[6:7], v42, s56, v[16:17]
	v_mad_u64_u32 v[44:45], s[6:7], v44, s56, v[16:17]
	v_mad_u64_u32 v[16:17], s[6:7], v47, s56, v[16:17]
	global_load_dword v32, v[32:33], off nt
	s_nop 0
	global_load_dword v33, v[34:35], off nt
	s_nop 0
	global_load_dword v34, v[36:37], off nt
	global_load_dword v35, v[38:39], off nt
	s_nop 0
	global_load_dword v36, v[40:41], off nt
	global_load_dword v37, v[42:43], off nt
	global_load_dword v38, v[44:45], off nt
	s_nop 0
	global_load_dword v16, v[16:17], off nt
	s_waitcnt vmcnt(0)
	ds_write2_b32 v19, v49, v50 offset1:66
	ds_write2_b32 v19, v51, v52 offset0:132 offset1:198
	ds_write2_b32 v25, v53, v54 offset0:8 offset1:74
	ds_write2_b32 v25, v55, v56 offset0:140 offset1:206
	ds_write2_b32 v26, v57, v58 offset0:16 offset1:82
	ds_write2_b32 v26, v59, v60 offset0:148 offset1:214
	ds_write2_b32 v27, v61, v62 offset0:24 offset1:90
	ds_write2_b32 v27, v63, v64 offset0:156 offset1:222
	ds_write2_b32 v28, v65, v66 offset0:32 offset1:98
	ds_write2_b32 v28, v67, v68 offset0:164 offset1:230
	ds_write2_b32 v29, v69, v70 offset0:40 offset1:106
	ds_write2_b32 v29, v71, v46 offset0:172 offset1:238
	ds_write2_b32 v30, v32, v33 offset0:48 offset1:114
	ds_write2_b32 v30, v34, v35 offset0:180 offset1:246
	ds_write2_b32 v31, v36, v37 offset0:56 offset1:122
	ds_write2_b32 v31, v38, v16 offset0:188 offset1:254
	s_waitcnt lgkmcnt(0)
	ds_read2_b32 v[16:17], v21 offset1:8
	ds_read2_b32 v[38:39], v21 offset0:33 offset1:41
	ds_read2_b32 v[40:41], v21 offset0:66 offset1:74
	ds_read2_b32 v[42:43], v21 offset0:99 offset1:107
	ds_read2_b32 v[44:45], v21 offset0:132 offset1:140
	s_waitcnt lgkmcnt(4)
	v_bfe_u32 v32, v16, 16, 1
	v_add3_u32 v16, v16, v32, s39
	s_waitcnt lgkmcnt(3)
	v_bfe_u32 v32, v38, 16, 1
	v_lshrrev_b32_e32 v16, 16, v16
	v_add3_u32 v32, v38, v32, s39
	ds_read2_b32 v[46:47], v21 offset0:165 offset1:173
	v_and_or_b32 v32, v32, s40, v16
	s_waitcnt lgkmcnt(3)
	v_bfe_u32 v16, v40, 16, 1
	v_add3_u32 v16, v40, v16, s39
	s_waitcnt lgkmcnt(2)
	v_bfe_u32 v33, v42, 16, 1
	ds_read2_b32 v[48:49], v21 offset0:198 offset1:206
	v_lshrrev_b32_e32 v16, 16, v16
	v_add3_u32 v33, v42, v33, s39
	ds_read2_b32 v[50:51], v21 offset0:231 offset1:239
	v_and_or_b32 v33, v33, s40, v16
	s_waitcnt lgkmcnt(3)
	v_bfe_u32 v16, v44, 16, 1
	v_add3_u32 v16, v44, v16, s39
	s_waitcnt lgkmcnt(2)
	v_bfe_u32 v34, v46, 16, 1
	v_lshrrev_b32_e32 v16, 16, v16
	v_add3_u32 v34, v46, v34, s39
	v_and_or_b32 v34, v34, s40, v16
	s_waitcnt lgkmcnt(1)
	v_bfe_u32 v16, v48, 16, 1
	v_add3_u32 v16, v48, v16, s39
	s_waitcnt lgkmcnt(0)
	v_bfe_u32 v35, v50, 16, 1
	v_lshrrev_b32_e32 v16, 16, v16
	v_add3_u32 v35, v50, v35, s39
	v_add_u32_e32 v52, s10, v20
	s_lshl_b32 s2, s12, 1
	v_and_or_b32 v35, v35, s40, v16
	v_ashrrev_i32_e32 v53, 31, v52
	v_bfe_u32 v16, v17, 16, 1
	v_lshl_add_u64 v[36:37], v[12:13], 0, s[2:3]
	v_lshlrev_b64 v[52:53], 11, v[52:53]
	v_add3_u32 v16, v17, v16, s39
	v_bfe_u32 v17, v39, 16, 1
	v_lshl_add_u64 v[52:53], v[36:37], 0, v[52:53]
	v_lshrrev_b32_e32 v16, 16, v16
	v_add3_u32 v17, v39, v17, s39
	global_store_dwordx4 v[52:53], v[32:35], off
	ds_read2_b32 v[38:39], v21 offset0:16 offset1:24
	v_add_u32_e32 v52, s10, v23
	v_and_or_b32 v32, v17, s40, v16
	v_bfe_u32 v16, v41, 16, 1
	v_add3_u32 v16, v41, v16, s39
	v_bfe_u32 v17, v43, 16, 1
	v_lshrrev_b32_e32 v16, 16, v16
	v_add3_u32 v17, v43, v17, s39
	v_and_or_b32 v33, v17, s40, v16
	v_bfe_u32 v16, v45, 16, 1
	v_add3_u32 v16, v45, v16, s39
	v_bfe_u32 v17, v47, 16, 1
	v_lshrrev_b32_e32 v16, 16, v16
	v_add3_u32 v17, v47, v17, s39
	v_and_or_b32 v34, v17, s40, v16
	v_bfe_u32 v16, v49, 16, 1
	v_add3_u32 v16, v49, v16, s39
	v_bfe_u32 v17, v51, 16, 1
	v_lshrrev_b32_e32 v16, 16, v16
	v_add3_u32 v17, v51, v17, s39
	v_and_or_b32 v35, v17, s40, v16
	v_add_u32_e32 v16, s10, v22
	v_ashrrev_i32_e32 v17, 31, v16
	v_lshlrev_b64 v[16:17], 11, v[16:17]
	v_lshl_add_u64 v[16:17], v[36:37], 0, v[16:17]
	global_store_dwordx4 v[16:17], v[32:35], off
	ds_read2_b32 v[16:17], v21 offset0:49 offset1:57
	ds_read2_b32 v[40:41], v21 offset0:82 offset1:90
	ds_read2_b32 v[42:43], v21 offset0:115 offset1:123
	s_waitcnt lgkmcnt(3)
	v_bfe_u32 v32, v38, 16, 1
	v_add3_u32 v32, v38, v32, s39
	s_waitcnt lgkmcnt(2)
	v_bfe_u32 v33, v16, 16, 1
	ds_read2_b32 v[44:45], v21 offset0:148 offset1:156
	v_lshrrev_b32_e32 v32, 16, v32
	v_add3_u32 v16, v16, v33, s39
	ds_read2_b32 v[46:47], v21 offset0:181 offset1:189
	v_and_or_b32 v32, v16, s40, v32
	s_waitcnt lgkmcnt(3)
	v_bfe_u32 v16, v40, 16, 1
	v_add3_u32 v16, v40, v16, s39
	s_waitcnt lgkmcnt(2)
	v_bfe_u32 v33, v42, 16, 1
	ds_read2_b32 v[48:49], v21 offset0:214 offset1:222
	v_lshrrev_b32_e32 v16, 16, v16
	v_add3_u32 v33, v42, v33, s39
	ds_read2_b32 v[50:51], v21 offset0:247 offset1:255
	v_and_or_b32 v33, v33, s40, v16
	s_waitcnt lgkmcnt(3)
	v_bfe_u32 v16, v44, 16, 1
	v_add3_u32 v16, v44, v16, s39
	s_waitcnt lgkmcnt(2)
	v_bfe_u32 v34, v46, 16, 1
	v_lshrrev_b32_e32 v16, 16, v16
	v_add3_u32 v34, v46, v34, s39
	v_and_or_b32 v34, v34, s40, v16
	s_waitcnt lgkmcnt(1)
	v_bfe_u32 v16, v48, 16, 1
	v_add3_u32 v16, v48, v16, s39
	s_waitcnt lgkmcnt(0)
	v_bfe_u32 v35, v50, 16, 1
	v_ashrrev_i32_e32 v53, 31, v52
	v_lshrrev_b32_e32 v16, 16, v16
	v_add3_u32 v35, v50, v35, s39
	v_lshlrev_b64 v[52:53], 11, v[52:53]
	v_and_or_b32 v35, v35, s40, v16
	v_lshl_add_u64 v[52:53], v[36:37], 0, v[52:53]
	v_bfe_u32 v16, v39, 16, 1
	global_store_dwordx4 v[52:53], v[32:35], off
	v_add3_u32 v16, v39, v16, s39
	v_lshrrev_b32_e32 v16, 16, v16
	v_bfe_u32 v32, v17, 16, 1
	v_add3_u32 v17, v17, v32, s39
	v_and_or_b32 v32, v17, s40, v16
	v_bfe_u32 v16, v41, 16, 1
	v_add3_u32 v16, v41, v16, s39
	v_bfe_u32 v17, v43, 16, 1
	v_lshrrev_b32_e32 v16, 16, v16
	v_add3_u32 v17, v43, v17, s39
	v_and_or_b32 v33, v17, s40, v16
	v_bfe_u32 v16, v45, 16, 1
	v_add3_u32 v16, v45, v16, s39
	v_bfe_u32 v17, v47, 16, 1
	v_lshrrev_b32_e32 v16, 16, v16
	v_add3_u32 v17, v47, v17, s39
	v_and_or_b32 v34, v17, s40, v16
	v_bfe_u32 v16, v49, 16, 1
	v_add3_u32 v16, v49, v16, s39
	v_bfe_u32 v17, v51, 16, 1
	v_lshrrev_b32_e32 v16, 16, v16
	v_add3_u32 v17, v51, v17, s39
	v_and_or_b32 v35, v17, s40, v16
	v_add_u32_e32 v16, s10, v24
	v_ashrrev_i32_e32 v17, 31, v16
	v_lshlrev_b64 v[16:17], 11, v[16:17]
	v_lshl_add_u64 v[16:17], v[36:37], 0, v[16:17]
	global_store_dwordx4 v[16:17], v[32:35], off
	s_waitcnt lgkmcnt(0)

.LBB0_86:
	s_andn2_b64 vcc, exec, s[6:7]
	s_cbranch_vccnz .LBB0_88
	s_waitcnt lgkmcnt(0)
	v_mov_b32_e32 v16, s57
	ds_read_b64 v[16:17], v16
	s_add_i32 s6, s14, 0xffff2e00
	s_add_i32 s2, s18, 0x1a00
	s_and_b32 s6, s6, 0x3e0
	s_and_b32 s2, s2, 0x1ffc0
	s_waitcnt lgkmcnt(0)
	v_readfirstlane_b32 s7, v16
	s_lshl_b32 s10, s6, 2
	v_readfirstlane_b32 s11, v17
	s_add_u32 s10, s7, s10
	v_or_b32_e32 v32, s2, v18
	s_addc_u32 s11, s11, 0
	v_lshl_add_u64 v[16:17], s[10:11], 0, v[2:3]
	v_lshlrev_b32_e32 v32, 12, v32
	v_mov_b32_e32 v33, v3
	v_lshl_add_u64 v[34:35], v[16:17], 0, v[32:33]
	v_add_co_u32_e32 v36, vcc, s24, v34
	v_or_b32_e32 v38, 0x4000, v32
	s_nop 0
	v_addc_co_u32_e32 v37, vcc, 0, v35, vcc
	v_add_co_u32_e32 v40, vcc, s28, v34
	v_mov_b32_e32 v39, v3
	s_nop 0
	v_addc_co_u32_e32 v41, vcc, 0, v35, vcc
	v_add_co_u32_e32 v44, vcc, s33, v34
	v_lshl_add_u64 v[38:39], v[16:17], 0, v[38:39]
	s_nop 0
	v_addc_co_u32_e32 v45, vcc, 0, v35, vcc
	v_add_co_u32_e32 v48, vcc, s37, v34
	v_or_b32_e32 v42, 0x8000, v32
	v_mov_b32_e32 v43, v3
	v_or_b32_e32 v46, 0xc000, v32
	v_mov_b32_e32 v47, v3
	v_addc_co_u32_e32 v49, vcc, 0, v35, vcc
	v_lshl_add_u64 v[42:43], v[16:17], 0, v[42:43]
	v_lshl_add_u64 v[46:47], v[16:17], 0, v[46:47]
	global_load_dword v52, v[34:35], off nt
	global_load_dword v53, v[36:37], off nt
	global_load_dword v54, v[38:39], off nt
	global_load_dword v55, v[40:41], off nt
	global_load_dword v56, v[42:43], off nt
	global_load_dword v57, v[44:45], off nt
	global_load_dword v58, v[46:47], off nt
	global_load_dword v59, v[48:49], off nt
	v_add_co_u32_e32 v38, vcc, s42, v34
	v_or_b32_e32 v36, 0x10000, v32
	s_nop 0
	v_addc_co_u32_e32 v39, vcc, 0, v35, vcc
	v_add_co_u32_e32 v42, vcc, s43, v34
	v_mov_b32_e32 v37, v3
	s_nop 0
	v_addc_co_u32_e32 v43, vcc, 0, v35, vcc
	v_add_co_u32_e32 v46, vcc, s44, v34
	v_lshl_add_u64 v[36:37], v[16:17], 0, v[36:37]
	s_nop 0
	v_addc_co_u32_e32 v47, vcc, 0, v35, vcc
	v_add_co_u32_e32 v50, vcc, s45, v34
	v_or_b32_e32 v40, 0x14000, v32
	v_mov_b32_e32 v41, v3
	v_or_b32_e32 v44, 0x18000, v32
	v_mov_b32_e32 v45, v3
	v_or_b32_e32 v48, 0x1c000, v32
	v_mov_b32_e32 v49, v3
	v_addc_co_u32_e32 v51, vcc, 0, v35, vcc
	v_lshl_add_u64 v[40:41], v[16:17], 0, v[40:41]
	v_lshl_add_u64 v[44:45], v[16:17], 0, v[44:45]
	v_lshl_add_u64 v[48:49], v[16:17], 0, v[48:49]
	global_load_dword v60, v[36:37], off nt
	global_load_dword v61, v[38:39], off nt
	global_load_dword v62, v[40:41], off nt
	global_load_dword v63, v[42:43], off nt
	global_load_dword v64, v[44:45], off nt
	global_load_dword v65, v[46:47], off nt
	global_load_dword v66, v[48:49], off nt
	global_load_dword v67, v[50:51], off nt
	v_add_co_u32_e32 v38, vcc, s46, v34
	v_or_b32_e32 v36, 0x20000, v32
	s_nop 0
	v_addc_co_u32_e32 v39, vcc, 0, v35, vcc
	v_add_co_u32_e32 v42, vcc, s47, v34
	v_mov_b32_e32 v37, v3
	s_nop 0
	v_addc_co_u32_e32 v43, vcc, 0, v35, vcc
	v_add_co_u32_e32 v46, vcc, s48, v34
	v_or_b32_e32 v48, 0x2c000, v32
	s_nop 0
	v_addc_co_u32_e32 v47, vcc, 0, v35, vcc
	v_mov_b32_e32 v49, v3
	v_add_co_u32_e32 v50, vcc, s49, v34
	v_lshl_add_u64 v[36:37], v[16:17], 0, v[36:37]
	v_or_b32_e32 v40, 0x24000, v32
	v_mov_b32_e32 v41, v3
	v_or_b32_e32 v44, 0x28000, v32
	v_mov_b32_e32 v45, v3
	v_lshl_add_u64 v[48:49], v[16:17], 0, v[48:49]
	v_addc_co_u32_e32 v51, vcc, 0, v35, vcc
	v_lshl_add_u64 v[40:41], v[16:17], 0, v[40:41]
	v_lshl_add_u64 v[44:45], v[16:17], 0, v[44:45]
	global_load_dword v68, v[36:37], off nt
	global_load_dword v69, v[38:39], off nt
	global_load_dword v70, v[40:41], off nt
	global_load_dword v71, v[42:43], off nt
	global_load_dword v72, v[44:45], off nt
	global_load_dword v73, v[46:47], off nt
	s_nop 0
	global_load_dword v48, v[48:49], off nt
	s_nop 0
	global_load_dword v49, v[50:51], off nt
	v_add_co_u32_e32 v38, vcc, s50, v34
	v_or_b32_e32 v36, 0x30000, v32
	s_nop 0
	v_addc_co_u32_e32 v39, vcc, 0, v35, vcc
	v_add_co_u32_e32 v42, vcc, s51, v34
	v_mov_b32_e32 v37, v3
	s_nop 0
	v_addc_co_u32_e32 v43, vcc, 0, v35, vcc
	v_add_co_u32_e32 v46, vcc, s52, v34
	v_or_b32_e32 v40, 0x34000, v32
	v_mov_b32_e32 v41, v3
	v_or_b32_e32 v44, 0x38000, v32
	v_mov_b32_e32 v45, v3
	v_addc_co_u32_e32 v47, vcc, 0, v35, vcc
	v_or_b32_e32 v32, 0x3c000, v32
	v_lshl_add_u64 v[36:37], v[16:17], 0, v[36:37]
	v_lshl_add_u64 v[40:41], v[16:17], 0, v[40:41]
	v_lshl_add_u64 v[44:45], v[16:17], 0, v[44:45]
	v_lshl_add_u64 v[16:17], v[16:17], 0, v[32:33]
	v_add_co_u32_e32 v32, vcc, s53, v34
	s_lshl_b32 s2, s2, 1
	s_nop 0
	v_addc_co_u32_e32 v33, vcc, 0, v35, vcc
	global_load_dword v34, v[36:37], off nt
	global_load_dword v35, v[38:39], off nt
	s_nop 0
	global_load_dword v36, v[40:41], off nt
	global_load_dword v37, v[42:43], off nt
	global_load_dword v38, v[44:45], off nt
	global_load_dword v39, v[46:47], off nt
	s_nop 0
	global_load_dword v16, v[16:17], off nt
	s_nop 0
	global_load_dword v17, v[32:33], off nt
	s_waitcnt vmcnt(0)
	ds_write2_b32 v19, v52, v53 offset1:66
	ds_write2_b32 v19, v54, v55 offset0:132 offset1:198
	ds_write2_b32 v25, v56, v57 offset0:8 offset1:74
	ds_write2_b32 v25, v58, v59 offset0:140 offset1:206
	ds_write2_b32 v26, v60, v61 offset0:16 offset1:82
	ds_write2_b32 v26, v62, v63 offset0:148 offset1:214
	ds_write2_b32 v27, v64, v65 offset0:24 offset1:90
	ds_write2_b32 v27, v66, v67 offset0:156 offset1:222
	ds_write2_b32 v28, v68, v69 offset0:32 offset1:98
	ds_write2_b32 v28, v70, v71 offset0:164 offset1:230
	ds_write2_b32 v29, v72, v73 offset0:40 offset1:106
	ds_write2_b32 v29, v48, v49 offset0:172 offset1:238
	ds_write2_b32 v30, v34, v35 offset0:48 offset1:114
	ds_write2_b32 v30, v36, v37 offset0:180 offset1:246
	ds_write2_b32 v31, v38, v39 offset0:56 offset1:122
	ds_write2_b32 v31, v16, v17 offset0:188 offset1:254
	s_waitcnt lgkmcnt(0)
	ds_read2_b32 v[16:17], v21 offset1:8
	ds_read2_b32 v[38:39], v21 offset0:33 offset1:41
	ds_read2_b32 v[40:41], v21 offset0:66 offset1:74
	ds_read2_b32 v[42:43], v21 offset0:99 offset1:107
	ds_read2_b32 v[44:45], v21 offset0:132 offset1:140
	s_waitcnt lgkmcnt(4)
	v_bfe_u32 v32, v16, 16, 1
	v_add3_u32 v16, v16, v32, s39
	s_waitcnt lgkmcnt(3)
	v_bfe_u32 v32, v38, 16, 1
	v_lshrrev_b32_e32 v16, 16, v16
	v_add3_u32 v32, v38, v32, s39
	ds_read2_b32 v[46:47], v21 offset0:165 offset1:173
	v_and_or_b32 v32, v32, s40, v16
	s_waitcnt lgkmcnt(3)
	v_bfe_u32 v16, v40, 16, 1
	v_add3_u32 v16, v40, v16, s39
	s_waitcnt lgkmcnt(2)
	v_bfe_u32 v33, v42, 16, 1
	ds_read2_b32 v[48:49], v21 offset0:198 offset1:206
	v_lshrrev_b32_e32 v16, 16, v16
	v_add3_u32 v33, v42, v33, s39
	ds_read2_b32 v[50:51], v21 offset0:231 offset1:239
	v_and_or_b32 v33, v33, s40, v16
	s_waitcnt lgkmcnt(3)
	v_bfe_u32 v16, v44, 16, 1
	v_add3_u32 v16, v44, v16, s39
	s_waitcnt lgkmcnt(2)
	v_bfe_u32 v34, v46, 16, 1
	v_lshrrev_b32_e32 v16, 16, v16
	v_add3_u32 v34, v46, v34, s39
	v_and_or_b32 v34, v34, s40, v16
	s_waitcnt lgkmcnt(1)
	v_bfe_u32 v16, v48, 16, 1
	v_add3_u32 v16, v48, v16, s39
	s_waitcnt lgkmcnt(0)
	v_bfe_u32 v35, v50, 16, 1
	v_lshrrev_b32_e32 v16, 16, v16
	v_add3_u32 v35, v50, v35, s39
	v_and_or_b32 v35, v35, s40, v16
	v_or_b32_e32 v16, s6, v20
	v_lshlrev_b32_e32 v52, 11, v16
	v_bfe_u32 v16, v17, 16, 1
	v_lshl_add_u64 v[36:37], v[14:15], 0, s[2:3]
	v_mov_b32_e32 v53, v3
	v_add3_u32 v16, v17, v16, s39
	v_bfe_u32 v17, v39, 16, 1
	v_lshl_add_u64 v[52:53], v[36:37], 0, v[52:53]
	v_lshrrev_b32_e32 v16, 16, v16
	v_add3_u32 v17, v39, v17, s39
	global_store_dwordx4 v[52:53], v[32:35], off
	ds_read2_b32 v[38:39], v21 offset0:16 offset1:24
	v_mov_b32_e32 v53, v3
	v_and_or_b32 v32, v17, s40, v16
	v_bfe_u32 v16, v41, 16, 1
	v_add3_u32 v16, v41, v16, s39
	v_bfe_u32 v17, v43, 16, 1
	v_lshrrev_b32_e32 v16, 16, v16
	v_add3_u32 v17, v43, v17, s39
	v_and_or_b32 v33, v17, s40, v16
	v_bfe_u32 v16, v45, 16, 1
	v_add3_u32 v16, v45, v16, s39
	v_bfe_u32 v17, v47, 16, 1
	v_lshrrev_b32_e32 v16, 16, v16
	v_add3_u32 v17, v47, v17, s39
	v_and_or_b32 v34, v17, s40, v16
	v_bfe_u32 v16, v49, 16, 1
	v_add3_u32 v16, v49, v16, s39
	v_bfe_u32 v17, v51, 16, 1
	v_lshrrev_b32_e32 v16, 16, v16
	v_add3_u32 v17, v51, v17, s39
	v_and_or_b32 v35, v17, s40, v16
	v_or_b32_e32 v16, s6, v22
	v_lshlrev_b32_e32 v16, 11, v16
	v_mov_b32_e32 v17, v3
	v_lshl_add_u64 v[16:17], v[36:37], 0, v[16:17]
	global_store_dwordx4 v[16:17], v[32:35], off
	ds_read2_b32 v[16:17], v21 offset0:49 offset1:57
	ds_read2_b32 v[40:41], v21 offset0:82 offset1:90
	ds_read2_b32 v[42:43], v21 offset0:115 offset1:123
	s_waitcnt lgkmcnt(3)
	v_bfe_u32 v32, v38, 16, 1
	v_add3_u32 v32, v38, v32, s39
	s_waitcnt lgkmcnt(2)
	v_bfe_u32 v33, v16, 16, 1
	ds_read2_b32 v[44:45], v21 offset0:148 offset1:156
	v_lshrrev_b32_e32 v32, 16, v32
	v_add3_u32 v16, v16, v33, s39
	ds_read2_b32 v[46:47], v21 offset0:181 offset1:189
	v_and_or_b32 v32, v16, s40, v32
	s_waitcnt lgkmcnt(3)
	v_bfe_u32 v16, v40, 16, 1
	v_add3_u32 v16, v40, v16, s39
	s_waitcnt lgkmcnt(2)
	v_bfe_u32 v33, v42, 16, 1
	ds_read2_b32 v[48:49], v21 offset0:214 offset1:222
	v_lshrrev_b32_e32 v16, 16, v16
	v_add3_u32 v33, v42, v33, s39
	ds_read2_b32 v[50:51], v21 offset0:247 offset1:255
	v_and_or_b32 v33, v33, s40, v16
	s_waitcnt lgkmcnt(3)
	v_bfe_u32 v16, v44, 16, 1
	v_add3_u32 v16, v44, v16, s39
	s_waitcnt lgkmcnt(2)
	v_bfe_u32 v34, v46, 16, 1
	v_lshrrev_b32_e32 v16, 16, v16
	v_add3_u32 v34, v46, v34, s39
	v_and_or_b32 v34, v34, s40, v16
	s_waitcnt lgkmcnt(1)
	v_bfe_u32 v16, v48, 16, 1
	v_add3_u32 v16, v48, v16, s39
	s_waitcnt lgkmcnt(0)
	v_bfe_u32 v35, v50, 16, 1
	v_lshrrev_b32_e32 v16, 16, v16
	v_add3_u32 v35, v50, v35, s39
	v_and_or_b32 v35, v35, s40, v16
	v_or_b32_e32 v16, s6, v23
	v_lshlrev_b32_e32 v52, 11, v16
	v_lshl_add_u64 v[52:53], v[36:37], 0, v[52:53]
	v_bfe_u32 v16, v39, 16, 1
	global_store_dwordx4 v[52:53], v[32:35], off
	v_add3_u32 v16, v39, v16, s39
	v_lshrrev_b32_e32 v16, 16, v16
	v_bfe_u32 v32, v17, 16, 1
	v_add3_u32 v17, v17, v32, s39
	v_and_or_b32 v32, v17, s40, v16
	v_bfe_u32 v16, v41, 16, 1
	v_add3_u32 v16, v41, v16, s39
	v_bfe_u32 v17, v43, 16, 1
	v_lshrrev_b32_e32 v16, 16, v16
	v_add3_u32 v17, v43, v17, s39
	v_and_or_b32 v33, v17, s40, v16
	v_bfe_u32 v16, v45, 16, 1
	v_add3_u32 v16, v45, v16, s39
	v_bfe_u32 v17, v47, 16, 1
	v_lshrrev_b32_e32 v16, 16, v16
	v_add3_u32 v17, v47, v17, s39
	v_and_or_b32 v34, v17, s40, v16
	v_bfe_u32 v16, v49, 16, 1
	v_add3_u32 v16, v49, v16, s39
	v_bfe_u32 v17, v51, 16, 1
	v_lshrrev_b32_e32 v16, 16, v16
	v_add3_u32 v17, v51, v17, s39
	v_and_or_b32 v35, v17, s40, v16
	v_add_lshl_u32 v16, s6, v24, 11
	v_mov_b32_e32 v17, v3
	v_lshl_add_u64 v[16:17], v[36:37], 0, v[16:17]
	global_store_dwordx4 v[16:17], v[32:35], off
	s_waitcnt lgkmcnt(0)

.LBB0_89:
	s_andn2_b64 vcc, exec, s[6:7]
	s_cbranch_vccnz .LBB0_66
	s_mul_hi_i32 s2, s61, 0x9c09c09d
	s_waitcnt lgkmcnt(0)
	v_mov_b32_e32 v16, s58
	s_add_i32 s2, s2, s61
	ds_read_b64 v[16:17], v16
	s_lshr_b32 s6, s2, 31
	s_ashr_i32 s2, s2, 6
	s_add_i32 s2, s2, s6
	s_lshl_b32 s10, s2, 6
	s_mulk_i32 s2, 0xf2e0
	s_add_i32 s6, s14, s2
	s_ashr_i32 s7, s6, 31
	s_waitcnt lgkmcnt(0)
	v_readfirstlane_b32 s11, v16
	s_lshl_b64 s[12:13], s[6:7], 2
	v_readfirstlane_b32 s62, v17
	s_add_u32 s12, s11, s12
	v_add_u32_e32 v16, s6, v0
	s_addc_u32 s13, s62, s13
	v_cmp_gt_i32_e32 vcc, s59, v16
	v_or_b32_e32 v32, s10, v18
	v_lshl_add_u64 v[16:17], s[12:13], 0, v[2:3]
	v_mov_b32_e32 v34, 0
	v_mov_b32_e32 v33, 0
	s_and_saveexec_b64 s[12:13], vcc
	s_cbranch_execz .LBB0_92
	v_mad_i64_i32 v[36:37], s[62:63], v32, s60, v[16:17]
	global_load_dword v33, v[36:37], off nt
.LBB0_92:
	s_or_b64 exec, exec, s[12:13]
	s_and_saveexec_b64 s[12:13], vcc
	s_cbranch_execz .LBB0_94
	v_add_u32_e32 v34, 2, v32
	v_mad_i64_i32 v[34:35], s[62:63], v34, s60, v[16:17]
	global_load_dword v34, v[34:35], off nt
.LBB0_94:
	s_or_b64 exec, exec, s[12:13]
	v_mov_b32_e32 v35, 0
	v_mov_b32_e32 v36, 0
	s_and_saveexec_b64 s[12:13], vcc
	s_cbranch_execz .LBB0_96
	v_add_u32_e32 v36, 4, v32
	v_mad_i64_i32 v[36:37], s[62:63], v36, s60, v[16:17]
	global_load_dword v36, v[36:37], off nt
.LBB0_96:
	s_or_b64 exec, exec, s[12:13]
	s_and_saveexec_b64 s[12:13], vcc
	s_cbranch_execz .LBB0_98
	v_add_u32_e32 v35, 6, v32
	v_mad_i64_i32 v[38:39], s[62:63], v35, s60, v[16:17]
	global_load_dword v35, v[38:39], off nt
.LBB0_98:
	s_or_b64 exec, exec, s[12:13]
	v_mov_b32_e32 v37, 0
	v_mov_b32_e32 v38, 0
	s_and_saveexec_b64 s[12:13], vcc
	s_cbranch_execz .LBB0_100
	v_add_u32_e32 v38, 8, v32
	v_mad_i64_i32 v[38:39], s[62:63], v38, s60, v[16:17]
	global_load_dword v38, v[38:39], off nt
.LBB0_100:
	s_or_b64 exec, exec, s[12:13]
	s_and_saveexec_b64 s[12:13], vcc
	s_cbranch_execz .LBB0_102
	v_add_u32_e32 v37, 10, v32
	v_mad_i64_i32 v[40:41], s[62:63], v37, s60, v[16:17]
	global_load_dword v37, v[40:41], off nt
.LBB0_102:
	s_or_b64 exec, exec, s[12:13]
	v_mov_b32_e32 v39, 0
	v_mov_b32_e32 v40, 0
	s_and_saveexec_b64 s[12:13], vcc
	s_cbranch_execz .LBB0_104
	v_add_u32_e32 v40, 12, v32
	v_mad_i64_i32 v[40:41], s[62:63], v40, s60, v[16:17]
	global_load_dword v40, v[40:41], off nt
.LBB0_104:
	s_or_b64 exec, exec, s[12:13]
	s_and_saveexec_b64 s[12:13], vcc
	s_cbranch_execz .LBB0_106
	v_add_u32_e32 v39, 14, v32
	v_mad_i64_i32 v[42:43], s[62:63], v39, s60, v[16:17]
	global_load_dword v39, v[42:43], off nt
.LBB0_106:
	s_or_b64 exec, exec, s[12:13]
	v_mov_b32_e32 v41, 0
	v_mov_b32_e32 v42, 0
	s_and_saveexec_b64 s[12:13], vcc
	s_cbranch_execz .LBB0_108
	v_add_u32_e32 v42, 16, v32
	v_mad_i64_i32 v[42:43], s[62:63], v42, s60, v[16:17]
	global_load_dword v42, v[42:43], off nt
.LBB0_108:
	s_or_b64 exec, exec, s[12:13]
	s_and_saveexec_b64 s[12:13], vcc
	s_cbranch_execz .LBB0_110
	v_add_u32_e32 v41, 18, v32
	v_mad_i64_i32 v[44:45], s[62:63], v41, s60, v[16:17]
	global_load_dword v41, v[44:45], off nt
.LBB0_110:
	s_or_b64 exec, exec, s[12:13]
	v_mov_b32_e32 v43, 0
	v_mov_b32_e32 v44, 0
	s_and_saveexec_b64 s[12:13], vcc
	s_cbranch_execz .LBB0_112
	v_add_u32_e32 v44, 20, v32
	v_mad_i64_i32 v[44:45], s[62:63], v44, s60, v[16:17]
	global_load_dword v44, v[44:45], off nt
.LBB0_112:
	s_or_b64 exec, exec, s[12:13]
	s_and_saveexec_b64 s[12:13], vcc
	s_cbranch_execz .LBB0_114
	v_add_u32_e32 v43, 22, v32
	v_mad_i64_i32 v[46:47], s[62:63], v43, s60, v[16:17]
	global_load_dword v43, v[46:47], off nt
.LBB0_114:
	s_or_b64 exec, exec, s[12:13]
	v_mov_b32_e32 v45, 0
	v_mov_b32_e32 v46, 0
	s_and_saveexec_b64 s[12:13], vcc
	s_cbranch_execz .LBB0_116
	v_add_u32_e32 v46, 24, v32
	v_mad_i64_i32 v[46:47], s[62:63], v46, s60, v[16:17]
	global_load_dword v46, v[46:47], off nt
.LBB0_116:
	s_or_b64 exec, exec, s[12:13]
	s_and_saveexec_b64 s[12:13], vcc
	s_cbranch_execz .LBB0_118
	v_add_u32_e32 v45, 26, v32
	v_mad_i64_i32 v[48:49], s[62:63], v45, s60, v[16:17]
	global_load_dword v45, v[48:49], off nt
.LBB0_118:
	s_or_b64 exec, exec, s[12:13]
	v_mov_b32_e32 v47, 0
	v_mov_b32_e32 v48, 0
	s_and_saveexec_b64 s[12:13], vcc
	s_cbranch_execz .LBB0_120
	v_add_u32_e32 v48, 28, v32
	v_mad_i64_i32 v[48:49], s[62:63], v48, s60, v[16:17]
	global_load_dword v48, v[48:49], off nt
.LBB0_120:
	s_or_b64 exec, exec, s[12:13]
	s_and_saveexec_b64 s[12:13], vcc
	s_cbranch_execz .LBB0_122
	v_add_u32_e32 v47, 30, v32
	v_mad_i64_i32 v[50:51], s[62:63], v47, s60, v[16:17]
	global_load_dword v47, v[50:51], off nt
.LBB0_122:
	s_or_b64 exec, exec, s[12:13]
	v_mov_b32_e32 v49, 0
	v_mov_b32_e32 v50, 0
	s_and_saveexec_b64 s[12:13], vcc
	s_cbranch_execz .LBB0_124
	v_add_u32_e32 v50, 32, v32
	v_mad_i64_i32 v[50:51], s[62:63], v50, s60, v[16:17]
	global_load_dword v50, v[50:51], off nt
.LBB0_124:
	s_or_b64 exec, exec, s[12:13]
	s_and_saveexec_b64 s[12:13], vcc
	s_cbranch_execz .LBB0_126
	v_add_u32_e32 v49, 34, v32
	v_mad_i64_i32 v[52:53], s[62:63], v49, s60, v[16:17]
	global_load_dword v49, v[52:53], off nt
.LBB0_126:
	s_or_b64 exec, exec, s[12:13]
	v_mov_b32_e32 v51, 0
	v_mov_b32_e32 v52, 0
	s_and_saveexec_b64 s[12:13], vcc
	s_cbranch_execz .LBB0_128
	v_add_u32_e32 v52, 36, v32
	v_mad_i64_i32 v[52:53], s[62:63], v52, s60, v[16:17]
	global_load_dword v52, v[52:53], off nt
.LBB0_128:
	s_or_b64 exec, exec, s[12:13]
	s_and_saveexec_b64 s[12:13], vcc
	s_cbranch_execz .LBB0_130
	v_add_u32_e32 v51, 38, v32
	v_mad_i64_i32 v[54:55], s[62:63], v51, s60, v[16:17]
	global_load_dword v51, v[54:55], off nt
.LBB0_130:
	s_or_b64 exec, exec, s[12:13]
	v_mov_b32_e32 v53, 0
	v_mov_b32_e32 v54, 0
	s_and_saveexec_b64 s[12:13], vcc
	s_cbranch_execz .LBB0_132
	v_add_u32_e32 v54, 40, v32
	v_mad_i64_i32 v[54:55], s[62:63], v54, s60, v[16:17]
	global_load_dword v54, v[54:55], off nt
.LBB0_132:
	s_or_b64 exec, exec, s[12:13]
	s_and_saveexec_b64 s[12:13], vcc
	s_cbranch_execz .LBB0_134
	v_add_u32_e32 v53, 42, v32
	v_mad_i64_i32 v[56:57], s[62:63], v53, s60, v[16:17]
	global_load_dword v53, v[56:57], off nt
.LBB0_134:
	s_or_b64 exec, exec, s[12:13]
	v_mov_b32_e32 v55, 0
	v_mov_b32_e32 v56, 0
	s_and_saveexec_b64 s[12:13], vcc
	s_cbranch_execz .LBB0_136
	v_add_u32_e32 v56, 44, v32
	v_mad_i64_i32 v[56:57], s[62:63], v56, s60, v[16:17]
	global_load_dword v56, v[56:57], off nt
.LBB0_136:
	s_or_b64 exec, exec, s[12:13]
	s_and_saveexec_b64 s[12:13], vcc
	s_cbranch_execz .LBB0_138
	v_add_u32_e32 v55, 46, v32
	v_mad_i64_i32 v[58:59], s[62:63], v55, s60, v[16:17]
	global_load_dword v55, v[58:59], off nt
.LBB0_138:
	s_or_b64 exec, exec, s[12:13]
	v_mov_b32_e32 v57, 0
	v_mov_b32_e32 v58, 0
	s_and_saveexec_b64 s[12:13], vcc
	s_cbranch_execz .LBB0_140
	v_add_u32_e32 v58, 48, v32
	v_mad_i64_i32 v[58:59], s[62:63], v58, s60, v[16:17]
	global_load_dword v58, v[58:59], off nt
.LBB0_140:
	s_or_b64 exec, exec, s[12:13]
	s_and_saveexec_b64 s[12:13], vcc
	s_cbranch_execz .LBB0_142
	v_add_u32_e32 v57, 50, v32
	v_mad_i64_i32 v[60:61], s[62:63], v57, s60, v[16:17]
	global_load_dword v57, v[60:61], off nt
.LBB0_142:
	s_or_b64 exec, exec, s[12:13]
	v_mov_b32_e32 v59, 0
	v_mov_b32_e32 v60, 0
	s_and_saveexec_b64 s[12:13], vcc
	s_cbranch_execz .LBB0_144
	v_add_u32_e32 v60, 52, v32
	v_mad_i64_i32 v[60:61], s[62:63], v60, s60, v[16:17]
	global_load_dword v60, v[60:61], off nt
.LBB0_144:
	s_or_b64 exec, exec, s[12:13]
	s_and_saveexec_b64 s[12:13], vcc
	s_cbranch_execz .LBB0_146
	v_add_u32_e32 v59, 54, v32
	v_mad_i64_i32 v[62:63], s[62:63], v59, s60, v[16:17]
	global_load_dword v59, v[62:63], off nt
.LBB0_146:
	s_or_b64 exec, exec, s[12:13]
	v_mov_b32_e32 v61, 0
	v_mov_b32_e32 v62, 0
	s_and_saveexec_b64 s[12:13], vcc
	s_cbranch_execz .LBB0_148
	v_add_u32_e32 v62, 56, v32
	v_mad_i64_i32 v[62:63], s[62:63], v62, s60, v[16:17]
	global_load_dword v62, v[62:63], off nt
.LBB0_148:
	s_or_b64 exec, exec, s[12:13]
	s_and_saveexec_b64 s[12:13], vcc
	s_cbranch_execz .LBB0_150
	v_add_u32_e32 v61, 58, v32
	v_mad_i64_i32 v[64:65], s[62:63], v61, s60, v[16:17]
	global_load_dword v61, v[64:65], off nt
.LBB0_150:
	s_or_b64 exec, exec, s[12:13]
	v_mov_b32_e32 v63, 0
	v_mov_b32_e32 v64, 0
	s_and_saveexec_b64 s[12:13], vcc
	s_cbranch_execz .LBB0_152
	v_add_u32_e32 v64, 60, v32
	v_mad_i64_i32 v[64:65], s[62:63], v64, s60, v[16:17]
	global_load_dword v64, v[64:65], off nt
.LBB0_152:
	s_or_b64 exec, exec, s[12:13]
	s_and_saveexec_b64 s[12:13], vcc
	s_cbranch_execz .LBB0_65
	v_add_u32_e32 v32, 62, v32
	v_mad_i64_i32 v[16:17], s[62:63], v32, s60, v[16:17]
	global_load_dword v63, v[16:17], off nt
	s_branch .LBB0_65

.LBB0_67_u:
	s_cmpk_gt_i32 s61, 0x68f
	s_mov_b64 s[6:7], -1
	s_cbranch_scc0 .LBB0_89_u
	s_cmpk_gt_u32 s61, 0x88f
	s_cbranch_scc0 .LBB0_86_u
	s_cmpk_gt_u32 s61, 0x138f
	s_cbranch_scc0 .LBB0_79_u
	s_cmpk_gt_u32 s61, 0x190f
	s_cbranch_scc0 .LBB0_76_u
	s_waitcnt lgkmcnt(0)
	v_mov_b32_e32 v16, s20
	ds_read_b64 v[16:17], v16
	s_cmpk_gt_u32 s61, 0x1a0f
	s_cbranch_scc0 .LBB0_73_u
	s_and_b32 s6, s14, 0xe0
	s_waitcnt lgkmcnt(0)
	v_readfirstlane_b32 s7, v16
	s_and_b32 s2, s16, 0x7c0
	s_lshl_b32 s10, s6, 2
	v_readfirstlane_b32 s11, v17
	s_add_u32 s10, s7, s10
	s_addc_u32 s11, s11, 0
	v_or_b32_e32 v34, s2, v18
	v_lshl_add_u64 v[32:33], s[10:11], 0, v[2:3]
	v_lshl_add_u64 v[32:33], v[32:33], 0, s[4:5]
	v_lshlrev_b32_e32 v34, 10, v34
	v_mov_b32_e32 v35, v3
	v_lshl_add_u64 v[36:37], v[32:33], 0, v[34:35]
	v_add_co_u32_e32 v40, vcc, s21, v36
	v_or_b32_e32 v38, 0x1000, v34
	s_nop 0
	v_addc_co_u32_e32 v41, vcc, 0, v37, vcc
	v_add_co_u32_e32 v44, vcc, s24, v36
	v_mov_b32_e32 v39, v3
	s_nop 0
	v_addc_co_u32_e32 v45, vcc, 0, v37, vcc
	v_add_co_u32_e32 v48, vcc, s25, v36
	v_or_b32_e32 v42, 0x2000, v34
	v_mov_b32_e32 v43, v3
	v_or_b32_e32 v46, 0x3000, v34
	v_mov_b32_e32 v47, v3
	v_addc_co_u32_e32 v49, vcc, 0, v37, vcc
	v_lshl_add_u64 v[38:39], v[32:33], 0, v[38:39]
	v_lshl_add_u64 v[42:43], v[32:33], 0, v[42:43]
	v_lshl_add_u64 v[46:47], v[32:33], 0, v[46:47]
	global_load_dword v54, v[36:37], off nt
	global_load_dword v55, v[36:37], off offset:2048 nt
	global_load_dword v56, v[38:39], off nt
	global_load_dword v57, v[40:41], off offset:2048 nt
	global_load_dword v58, v[42:43], off nt
	global_load_dword v59, v[44:45], off offset:2048 nt
	global_load_dword v60, v[46:47], off nt
	global_load_dword v61, v[48:49], off offset:2048 nt
	v_add_co_u32_e32 v40, vcc, s26, v36
	v_or_b32_e32 v38, 0x4000, v34
	s_nop 0
	v_addc_co_u32_e32 v41, vcc, 0, v37, vcc
	v_add_co_u32_e32 v44, vcc, s27, v36
	v_mov_b32_e32 v39, v3
	s_nop 0
	v_addc_co_u32_e32 v45, vcc, 0, v37, vcc
	v_add_co_u32_e32 v48, vcc, s28, v36
	v_lshl_add_u64 v[38:39], v[32:33], 0, v[38:39]
	s_nop 0
	v_addc_co_u32_e32 v49, vcc, 0, v37, vcc
	v_add_co_u32_e32 v52, vcc, s29, v36
	v_or_b32_e32 v42, 0x5000, v34
	v_mov_b32_e32 v43, v3
	v_or_b32_e32 v46, 0x6000, v34
	v_mov_b32_e32 v47, v3
	v_or_b32_e32 v50, 0x7000, v34
	v_mov_b32_e32 v51, v3
	v_addc_co_u32_e32 v53, vcc, 0, v37, vcc
	v_lshl_add_u64 v[42:43], v[32:33], 0, v[42:43]
	v_lshl_add_u64 v[46:47], v[32:33], 0, v[46:47]
	v_lshl_add_u64 v[50:51], v[32:33], 0, v[50:51]
	global_load_dword v62, v[38:39], off nt
	global_load_dword v63, v[40:41], off offset:2048 nt
	global_load_dword v64, v[42:43], off nt
	global_load_dword v65, v[44:45], off offset:2048 nt
	global_load_dword v66, v[46:47], off nt
	global_load_dword v67, v[48:49], off offset:2048 nt
	global_load_dword v68, v[50:51], off nt
	global_load_dword v69, v[52:53], off offset:2048 nt
	v_add_co_u32_e32 v40, vcc, s30, v36
	v_or_b32_e32 v38, 0x8000, v34
	s_nop 0
	v_addc_co_u32_e32 v41, vcc, 0, v37, vcc
	v_add_co_u32_e32 v44, vcc, s31, v36
	v_mov_b32_e32 v39, v3
	s_nop 0
	v_addc_co_u32_e32 v45, vcc, 0, v37, vcc
	v_add_co_u32_e32 v48, vcc, s33, v36
	v_or_b32_e32 v50, 0xb000, v34
	s_nop 0
	v_addc_co_u32_e32 v49, vcc, 0, v37, vcc
	v_mov_b32_e32 v51, v3
	v_add_co_u32_e32 v52, vcc, s34, v36
	v_lshl_add_u64 v[38:39], v[32:33], 0, v[38:39]
	v_or_b32_e32 v42, 0x9000, v34
	v_mov_b32_e32 v43, v3
	v_or_b32_e32 v46, 0xa000, v34
	v_mov_b32_e32 v47, v3
	v_lshl_add_u64 v[50:51], v[32:33], 0, v[50:51]
	v_addc_co_u32_e32 v53, vcc, 0, v37, vcc
	v_lshl_add_u64 v[42:43], v[32:33], 0, v[42:43]
	v_lshl_add_u64 v[46:47], v[32:33], 0, v[46:47]
	global_load_dword v70, v[38:39], off nt
	global_load_dword v71, v[40:41], off offset:2048 nt
	global_load_dword v72, v[42:43], off nt
	global_load_dword v73, v[44:45], off offset:2048 nt
	global_load_dword v74, v[46:47], off nt
	global_load_dword v75, v[48:49], off offset:2048 nt
	s_nop 0
	global_load_dword v50, v[50:51], off nt
	s_nop 0
	global_load_dword v51, v[52:53], off offset:2048 nt
	v_add_co_u32_e32 v40, vcc, s35, v36
	v_or_b32_e32 v38, 0xc000, v34
	s_nop 0
	v_addc_co_u32_e32 v41, vcc, 0, v37, vcc
	v_add_co_u32_e32 v44, vcc, s36, v36
	v_mov_b32_e32 v39, v3
	s_nop 0
	v_addc_co_u32_e32 v45, vcc, 0, v37, vcc
	v_add_co_u32_e32 v48, vcc, s37, v36
	v_or_b32_e32 v42, 0xd000, v34
	v_mov_b32_e32 v43, v3
	v_or_b32_e32 v46, 0xe000, v34
	v_mov_b32_e32 v47, v3
	v_addc_co_u32_e32 v49, vcc, 0, v37, vcc
	v_or_b32_e32 v34, 0xf000, v34
	v_lshl_add_u64 v[38:39], v[32:33], 0, v[38:39]
	v_lshl_add_u64 v[42:43], v[32:33], 0, v[42:43]
	v_lshl_add_u64 v[46:47], v[32:33], 0, v[46:47]
	v_lshl_add_u64 v[32:33], v[32:33], 0, v[34:35]
	v_add_co_u32_e32 v34, vcc, s38, v36
	s_lshl_b32 s2, s2, 1
	s_nop 0
	v_addc_co_u32_e32 v35, vcc, 0, v37, vcc
	global_load_dword v36, v[38:39], off nt
	global_load_dword v37, v[40:41], off offset:2048 nt
	s_nop 0
	global_load_dword v38, v[42:43], off nt
	global_load_dword v39, v[44:45], off offset:2048 nt
	global_load_dword v40, v[46:47], off nt
	global_load_dword v41, v[48:49], off offset:2048 nt
	s_nop 0
	global_load_dword v32, v[32:33], off nt
	s_nop 0
	global_load_dword v33, v[34:35], off offset:2048 nt
	s_waitcnt vmcnt(0)
	ds_write2_b32 v19, v54, v55 offset1:66
	ds_write2_b32 v19, v56, v57 offset0:132 offset1:198
	ds_write2_b32 v25, v58, v59 offset0:8 offset1:74
	ds_write2_b32 v25, v60, v61 offset0:140 offset1:206
	ds_write2_b32 v26, v62, v63 offset0:16 offset1:82
	ds_write2_b32 v26, v64, v65 offset0:148 offset1:214
	ds_write2_b32 v27, v66, v67 offset0:24 offset1:90
	ds_write2_b32 v27, v68, v69 offset0:156 offset1:222
	ds_write2_b32 v28, v70, v71 offset0:32 offset1:98
	ds_write2_b32 v28, v72, v73 offset0:164 offset1:230
	ds_write2_b32 v29, v74, v75 offset0:40 offset1:106
	ds_write2_b32 v29, v50, v51 offset0:172 offset1:238
	ds_write2_b32 v30, v36, v37 offset0:48 offset1:114
	ds_write2_b32 v30, v38, v39 offset0:180 offset1:246
	ds_write2_b32 v31, v40, v41 offset0:56 offset1:122
	ds_write2_b32 v31, v32, v33 offset0:188 offset1:254
	s_waitcnt lgkmcnt(0)
	ds_read2_b32 v[36:37], v21 offset1:8
	ds_read2_b32 v[40:41], v21 offset0:33 offset1:41
	ds_read2_b32 v[42:43], v21 offset0:66 offset1:74
	ds_read2_b32 v[44:45], v21 offset0:99 offset1:107
	ds_read2_b32 v[46:47], v21 offset0:132 offset1:140
	s_waitcnt lgkmcnt(4)
	v_bfe_u32 v32, v36, 16, 1
	v_add3_u32 v32, v36, v32, s39
	s_waitcnt lgkmcnt(3)
	v_bfe_u32 v33, v40, 16, 1
	v_lshrrev_b32_e32 v32, 16, v32
	v_add3_u32 v33, v40, v33, s39
	ds_read2_b32 v[48:49], v21 offset0:165 offset1:173
	v_and_or_b32 v32, v33, s40, v32
	s_waitcnt lgkmcnt(3)
	v_bfe_u32 v33, v42, 16, 1
	v_add3_u32 v33, v42, v33, s39
	s_waitcnt lgkmcnt(2)
	v_bfe_u32 v34, v44, 16, 1
	ds_read2_b32 v[50:51], v21 offset0:198 offset1:206
	v_lshrrev_b32_e32 v33, 16, v33
	v_add3_u32 v34, v44, v34, s39
	ds_read2_b32 v[52:53], v21 offset0:231 offset1:239
	v_and_or_b32 v33, v34, s40, v33
	s_waitcnt lgkmcnt(3)
	v_bfe_u32 v34, v46, 16, 1
	v_add3_u32 v34, v46, v34, s39
	s_waitcnt lgkmcnt(2)
	v_bfe_u32 v35, v48, 16, 1
	v_lshrrev_b32_e32 v34, 16, v34
	v_add3_u32 v35, v48, v35, s39
	v_and_or_b32 v34, v35, s40, v34
	s_waitcnt lgkmcnt(1)
	v_bfe_u32 v35, v50, 16, 1
	v_add3_u32 v35, v50, v35, s39
	s_waitcnt lgkmcnt(0)
	v_bfe_u32 v36, v52, 16, 1
	v_lshrrev_b32_e32 v35, 16, v35
	v_add3_u32 v36, v52, v36, s39
	v_and_or_b32 v35, v36, s40, v35
	v_or_b32_e32 v36, s6, v20
	v_lshl_add_u64 v[38:39], v[6:7], 0, s[2:3]
	v_lshlrev_b32_e32 v54, 12, v36
	v_mov_b32_e32 v55, v3
	v_lshl_add_u64 v[54:55], v[38:39], 0, v[54:55]
	global_store_dwordx4 v[54:55], v[32:35], off
	v_bfe_u32 v36, v53, 16, 1
	v_add3_u32 v36, v53, v36, s39
	v_bfe_u32 v32, v37, 16, 1
	v_add3_u32 v32, v37, v32, s39
	v_bfe_u32 v33, v41, 16, 1
	v_lshrrev_b32_e32 v32, 16, v32
	v_add3_u32 v33, v41, v33, s39
	v_and_or_b32 v32, v33, s40, v32
	v_bfe_u32 v33, v43, 16, 1
	v_add3_u32 v33, v43, v33, s39
	v_bfe_u32 v34, v45, 16, 1
	v_lshrrev_b32_e32 v33, 16, v33
	v_add3_u32 v34, v45, v34, s39
	v_and_or_b32 v33, v34, s40, v33
	v_bfe_u32 v34, v47, 16, 1
	v_add3_u32 v34, v47, v34, s39
	v_bfe_u32 v35, v49, 16, 1
	v_lshrrev_b32_e32 v34, 16, v34
	v_add3_u32 v35, v49, v35, s39
	v_and_or_b32 v34, v35, s40, v34
	v_bfe_u32 v35, v51, 16, 1
	v_add3_u32 v35, v51, v35, s39
	v_lshrrev_b32_e32 v35, 16, v35
	v_and_or_b32 v35, v36, s40, v35
	v_or_b32_e32 v36, s6, v22
	v_lshlrev_b32_e32 v36, 12, v36
	v_mov_b32_e32 v37, v3
	ds_read2_b32 v[40:41], v21 offset0:16 offset1:24
	v_lshl_add_u64 v[36:37], v[38:39], 0, v[36:37]
	global_store_dwordx4 v[36:37], v[32:35], off
	ds_read2_b32 v[36:37], v21 offset0:49 offset1:57
	ds_read2_b32 v[42:43], v21 offset0:82 offset1:90
	ds_read2_b32 v[44:45], v21 offset0:115 offset1:123
	s_waitcnt lgkmcnt(3)
	v_bfe_u32 v32, v40, 16, 1
	v_add3_u32 v32, v40, v32, s39
	s_waitcnt lgkmcnt(2)
	v_bfe_u32 v33, v36, 16, 1
	ds_read2_b32 v[46:47], v21 offset0:148 offset1:156
	v_lshrrev_b32_e32 v32, 16, v32
	v_add3_u32 v33, v36, v33, s39
	ds_read2_b32 v[48:49], v21 offset0:181 offset1:189
	v_and_or_b32 v32, v33, s40, v32
	s_waitcnt lgkmcnt(3)
	v_bfe_u32 v33, v42, 16, 1
	v_add3_u32 v33, v42, v33, s39
	s_waitcnt lgkmcnt(2)
	v_bfe_u32 v34, v44, 16, 1
	ds_read2_b32 v[50:51], v21 offset0:214 offset1:222
	v_lshrrev_b32_e32 v33, 16, v33
	v_add3_u32 v34, v44, v34, s39
	ds_read2_b32 v[52:53], v21 offset0:247 offset1:255
	v_and_or_b32 v33, v34, s40, v33
	s_waitcnt lgkmcnt(3)
	v_bfe_u32 v34, v46, 16, 1
	v_add3_u32 v34, v46, v34, s39
	s_waitcnt lgkmcnt(2)
	v_bfe_u32 v35, v48, 16, 1
	v_lshrrev_b32_e32 v34, 16, v34
	v_add3_u32 v35, v48, v35, s39
	v_and_or_b32 v34, v35, s40, v34
	s_waitcnt lgkmcnt(1)
	v_bfe_u32 v35, v50, 16, 1
	v_add3_u32 v35, v50, v35, s39
	s_waitcnt lgkmcnt(0)
	v_bfe_u32 v36, v52, 16, 1
	v_lshrrev_b32_e32 v35, 16, v35
	v_add3_u32 v36, v52, v36, s39
	v_and_or_b32 v35, v36, s40, v35
	v_or_b32_e32 v36, s6, v23
	v_lshlrev_b32_e32 v54, 12, v36
	v_mov_b32_e32 v55, v3
	v_lshl_add_u64 v[54:55], v[38:39], 0, v[54:55]
	global_store_dwordx4 v[54:55], v[32:35], off
	v_bfe_u32 v36, v53, 16, 1
	v_add3_u32 v36, v53, v36, s39
	v_bfe_u32 v32, v41, 16, 1
	v_add3_u32 v32, v41, v32, s39
	v_bfe_u32 v33, v37, 16, 1
	v_lshrrev_b32_e32 v32, 16, v32
	v_add3_u32 v33, v37, v33, s39
	v_and_or_b32 v32, v33, s40, v32
	v_bfe_u32 v33, v43, 16, 1
	v_add3_u32 v33, v43, v33, s39
	v_bfe_u32 v34, v45, 16, 1
	v_lshrrev_b32_e32 v33, 16, v33
	v_add3_u32 v34, v45, v34, s39
	v_and_or_b32 v33, v34, s40, v33
	v_bfe_u32 v34, v47, 16, 1
	v_add3_u32 v34, v47, v34, s39
	v_bfe_u32 v35, v49, 16, 1
	v_lshrrev_b32_e32 v34, 16, v34
	v_add3_u32 v35, v49, v35, s39
	v_and_or_b32 v34, v35, s40, v34
	v_bfe_u32 v35, v51, 16, 1
	v_add3_u32 v35, v51, v35, s39
	v_lshrrev_b32_e32 v35, 16, v35
	v_and_or_b32 v35, v36, s40, v35
	v_add_lshl_u32 v36, s6, v24, 12
	v_mov_b32_e32 v37, v3
	v_lshl_add_u64 v[36:37], v[38:39], 0, v[36:37]
	global_store_dwordx4 v[36:37], v[32:35], off
	s_waitcnt lgkmcnt(0)
	s_mov_b64 s[6:7], 0

.LBB0_152_u:
	s_or_b64 exec, exec, s[12:13]
	s_and_saveexec_b64 s[12:13], vcc
	s_cbranch_execz .LBB0_65_u
	v_add_u32_e32 v32, 62, v32
	v_mad_i64_i32 v[16:17], s[62:63], v32, s60, v[16:17]
	global_load_dword v63, v[16:17], off nt
	s_branch .LBB0_65_u
	s_nop 0
	s_nop 0
	s_nop 0
	s_nop 0
	s_nop 0
	s_nop 0
	s_nop 0
	s_nop 0
	s_nop 0
	s_nop 0
	s_nop 0
	s_nop 0
	s_nop 0
	s_nop 0
	s_nop 0
	s_nop 0
	s_nop 0
	s_nop 0
	s_nop 0
	s_nop 0

.LBB0_577:
	s_ashr_i32 s21, s34, 31
	s_lshr_b32 s21, s21, 29
	v_lshl_add_u32 v156, s34, 8, v158
	v_lshl_or_b32 v164, s58, 8, v160
	s_add_i32 s21, s34, s21
	s_ashr_i32 s21, s21, 3
	v_ashrrev_i32_e32 v165, 31, v164
	s_mul_hi_i32 s23, s21, 0x6000
	s_mulk_i32 s21, 0x6000
	s_add_u32 s36, s50, s21
	v_lshlrev_b32_e32 v157, 12, v156
	s_addc_u32 s37, s51, s23
	v_lshl_add_u32 v157, v164, 2, v157
	v_lshl_add_u64 v[128:129], v[164:165], 2, s[36:37]
	s_nop 0
	global_load_dwordx4 v[140:143], v[128:129], off
	global_load_dwordx4 v[136:139], v[128:129], off offset:64
	global_load_dwordx4 v[132:135], v[128:129], off offset:512
	s_nop 0
	global_load_dwordx4 v[128:131], v[128:129], off offset:576
	s_andn2_b64 vcc, exec, s[10:11]
	s_mov_b64 s[10:11], -1
	v_add_u32_e32 v164, 0x10000, v157
	v_add_u32_e32 v165, 0x20000, v157
	v_add_u32_e32 v166, 0x30000, v157
	v_add_u32_e32 v167, 0x80000, v157
	v_add_u32_e32 v168, 0x90000, v157
	v_add_u32_e32 v169, 0xa0000, v157
	v_add_u32_e32 v170, 0xb0000, v157
	global_load_dwordx4 v[172:175], v157, s[0:1] nt
	global_load_dwordx4 v[176:179], v157, s[0:1] offset:64 nt
	global_load_dwordx4 v[180:183], v157, s[0:1] offset:512 nt
	global_load_dwordx4 v[184:187], v157, s[0:1] offset:576 nt
	global_load_dwordx4 v[188:191], v164, s[0:1] nt
	global_load_dwordx4 v[192:195], v164, s[0:1] offset:64 nt
	global_load_dwordx4 v[196:199], v164, s[0:1] offset:512 nt
	global_load_dwordx4 v[200:203], v164, s[0:1] offset:576 nt
	global_load_dwordx4 v[204:207], v165, s[0:1] nt
	global_load_dwordx4 v[208:211], v165, s[0:1] offset:64 nt
	global_load_dwordx4 v[212:215], v165, s[0:1] offset:512 nt
	global_load_dwordx4 v[216:219], v165, s[0:1] offset:576 nt
	s_waitcnt vmcnt(11)
	v_pk_fma_f32 v[124:125], v[124:125], v[140:141], v[172:173]
	v_pk_fma_f32 v[126:127], v[126:127], v[142:143], v[174:175]
	global_store_dwordx4 v157, v[124:127], s[2:3] sc1
	global_load_dwordx4 v[172:175], v166, s[0:1] nt
	s_waitcnt vmcnt(12)
	v_pk_fma_f32 v[120:121], v[120:121], v[136:137], v[176:177]
	v_pk_fma_f32 v[122:123], v[122:123], v[138:139], v[178:179]
	global_store_dwordx4 v157, v[120:123], s[2:3] offset:64 sc1
	global_load_dwordx4 v[176:179], v166, s[0:1] offset:64 nt
	s_waitcnt vmcnt(13)
	v_pk_fma_f32 v[116:117], v[116:117], v[132:133], v[180:181]
	v_pk_fma_f32 v[118:119], v[118:119], v[134:135], v[182:183]
	global_store_dwordx4 v157, v[116:119], s[2:3] offset:512 sc1
	global_load_dwordx4 v[180:183], v166, s[0:1] offset:512 nt
	s_waitcnt vmcnt(14)
	v_pk_fma_f32 v[104:105], v[104:105], v[128:129], v[184:185]
	v_pk_fma_f32 v[106:107], v[106:107], v[130:131], v[186:187]
	global_store_dwordx4 v157, v[104:107], s[2:3] offset:576 sc1
	global_load_dwordx4 v[184:187], v166, s[0:1] offset:576 nt
	s_waitcnt vmcnt(15)
	v_pk_fma_f32 v[112:113], v[112:113], v[140:141], v[188:189]
	v_pk_fma_f32 v[114:115], v[114:115], v[142:143], v[190:191]
	global_store_dwordx4 v164, v[112:115], s[2:3] sc1
	global_load_dwordx4 v[188:191], v167, s[0:1] nt
	s_waitcnt vmcnt(16)
	v_pk_fma_f32 v[108:109], v[108:109], v[136:137], v[192:193]
	v_pk_fma_f32 v[110:111], v[110:111], v[138:139], v[194:195]
	global_store_dwordx4 v164, v[108:111], s[2:3] offset:64 sc1
	global_load_dwordx4 v[192:195], v167, s[0:1] offset:64 nt
	s_waitcnt vmcnt(17)
	v_pk_fma_f32 v[100:101], v[100:101], v[132:133], v[196:197]
	v_pk_fma_f32 v[102:103], v[102:103], v[134:135], v[198:199]
	global_store_dwordx4 v164, v[100:103], s[2:3] offset:512 sc1
	global_load_dwordx4 v[196:199], v167, s[0:1] offset:512 nt
	s_waitcnt vmcnt(18)
	v_pk_fma_f32 v[88:89], v[88:89], v[128:129], v[200:201]
	v_pk_fma_f32 v[90:91], v[90:91], v[130:131], v[202:203]
	global_store_dwordx4 v164, v[88:91], s[2:3] offset:576 sc1
	global_load_dwordx4 v[200:203], v167, s[0:1] offset:576 nt
	s_waitcnt vmcnt(19)
	v_pk_fma_f32 v[96:97], v[96:97], v[140:141], v[204:205]
	v_pk_fma_f32 v[98:99], v[98:99], v[142:143], v[206:207]
	global_store_dwordx4 v165, v[96:99], s[2:3] sc1
	global_load_dwordx4 v[204:207], v168, s[0:1] nt
	s_waitcnt vmcnt(20)
	v_pk_fma_f32 v[92:93], v[92:93], v[136:137], v[208:209]
	v_pk_fma_f32 v[94:95], v[94:95], v[138:139], v[210:211]
	global_store_dwordx4 v165, v[92:95], s[2:3] offset:64 sc1
	global_load_dwordx4 v[208:211], v168, s[0:1] offset:64 nt
	s_waitcnt vmcnt(21)
	v_pk_fma_f32 v[84:85], v[84:85], v[132:133], v[212:213]
	v_pk_fma_f32 v[86:87], v[86:87], v[134:135], v[214:215]
	global_store_dwordx4 v165, v[84:87], s[2:3] offset:512 sc1
	global_load_dwordx4 v[212:215], v168, s[0:1] offset:512 nt
	s_waitcnt vmcnt(22)
	v_pk_fma_f32 v[72:73], v[72:73], v[128:129], v[216:217]
	v_pk_fma_f32 v[74:75], v[74:75], v[130:131], v[218:219]
	global_store_dwordx4 v165, v[72:75], s[2:3] offset:576 sc1
	global_load_dwordx4 v[216:219], v168, s[0:1] offset:576 nt
	s_waitcnt vmcnt(22)
	v_pk_fma_f32 v[80:81], v[80:81], v[140:141], v[172:173]
	v_pk_fma_f32 v[82:83], v[82:83], v[142:143], v[174:175]
	global_store_dwordx4 v166, v[80:83], s[2:3] sc1
	global_load_dwordx4 v[172:175], v169, s[0:1] nt
	s_waitcnt vmcnt(22)
	v_pk_fma_f32 v[76:77], v[76:77], v[136:137], v[176:177]
	v_pk_fma_f32 v[78:79], v[78:79], v[138:139], v[178:179]
	global_store_dwordx4 v166, v[76:79], s[2:3] offset:64 sc1
	global_load_dwordx4 v[176:179], v169, s[0:1] offset:64 nt
	s_waitcnt vmcnt(22)
	v_pk_fma_f32 v[68:69], v[68:69], v[132:133], v[180:181]
	v_pk_fma_f32 v[70:71], v[70:71], v[134:135], v[182:183]
	global_store_dwordx4 v166, v[68:71], s[2:3] offset:512 sc1
	global_load_dwordx4 v[180:183], v169, s[0:1] offset:512 nt
	s_waitcnt vmcnt(22)
	v_pk_fma_f32 v[64:65], v[64:65], v[128:129], v[184:185]
	v_pk_fma_f32 v[66:67], v[66:67], v[130:131], v[186:187]
	global_store_dwordx4 v166, v[64:67], s[2:3] offset:576 sc1
	global_load_dwordx4 v[184:187], v169, s[0:1] offset:576 nt
	s_waitcnt vmcnt(22)
	v_pk_fma_f32 v[60:61], v[60:61], v[140:141], v[188:189]
	v_pk_fma_f32 v[62:63], v[62:63], v[142:143], v[190:191]
	global_store_dwordx4 v167, v[60:63], s[2:3] sc1
	global_load_dwordx4 v[188:191], v170, s[0:1] nt
	s_waitcnt vmcnt(22)
	v_pk_fma_f32 v[56:57], v[56:57], v[136:137], v[192:193]
	v_pk_fma_f32 v[58:59], v[58:59], v[138:139], v[194:195]
	global_store_dwordx4 v167, v[56:59], s[2:3] offset:64 sc1
	global_load_dwordx4 v[192:195], v170, s[0:1] offset:64 nt
	s_waitcnt vmcnt(22)
	v_pk_fma_f32 v[52:53], v[52:53], v[132:133], v[196:197]
	v_pk_fma_f32 v[54:55], v[54:55], v[134:135], v[198:199]
	global_store_dwordx4 v167, v[52:55], s[2:3] offset:512 sc1
	global_load_dwordx4 v[196:199], v170, s[0:1] offset:512 nt
	s_waitcnt vmcnt(22)
	v_pk_fma_f32 v[40:41], v[40:41], v[128:129], v[200:201]
	v_pk_fma_f32 v[42:43], v[42:43], v[130:131], v[202:203]
	global_store_dwordx4 v167, v[40:43], s[2:3] offset:576 sc1
	global_load_dwordx4 v[200:203], v170, s[0:1] offset:576 nt
	s_waitcnt vmcnt(22)
	v_pk_fma_f32 v[48:49], v[48:49], v[140:141], v[204:205]
	v_pk_fma_f32 v[50:51], v[50:51], v[142:143], v[206:207]
	global_store_dwordx4 v168, v[48:51], s[2:3] sc1
	s_waitcnt vmcnt(21)
	v_pk_fma_f32 v[44:45], v[44:45], v[136:137], v[208:209]
	v_pk_fma_f32 v[46:47], v[46:47], v[138:139], v[210:211]
	global_store_dwordx4 v168, v[44:47], s[2:3] offset:64 sc1
	s_waitcnt vmcnt(20)
	v_pk_fma_f32 v[36:37], v[36:37], v[132:133], v[212:213]
	v_pk_fma_f32 v[38:39], v[38:39], v[134:135], v[214:215]
	global_store_dwordx4 v168, v[36:39], s[2:3] offset:512 sc1
	s_waitcnt vmcnt(19)
	v_pk_fma_f32 v[24:25], v[24:25], v[128:129], v[216:217]
	v_pk_fma_f32 v[26:27], v[26:27], v[130:131], v[218:219]
	global_store_dwordx4 v168, v[24:27], s[2:3] offset:576 sc1
	s_waitcnt vmcnt(18)
	v_pk_fma_f32 v[32:33], v[32:33], v[140:141], v[172:173]
	v_pk_fma_f32 v[34:35], v[34:35], v[142:143], v[174:175]
	global_store_dwordx4 v169, v[32:35], s[2:3] sc1
	s_waitcnt vmcnt(17)
	v_pk_fma_f32 v[28:29], v[28:29], v[136:137], v[176:177]
	v_pk_fma_f32 v[30:31], v[30:31], v[138:139], v[178:179]
	global_store_dwordx4 v169, v[28:31], s[2:3] offset:64 sc1
	s_waitcnt vmcnt(16)
	v_pk_fma_f32 v[20:21], v[20:21], v[132:133], v[180:181]
	v_pk_fma_f32 v[22:23], v[22:23], v[134:135], v[182:183]
	global_store_dwordx4 v169, v[20:23], s[2:3] offset:512 sc1
	s_waitcnt vmcnt(15)
	v_pk_fma_f32 v[8:9], v[8:9], v[128:129], v[184:185]
	v_pk_fma_f32 v[10:11], v[10:11], v[130:131], v[186:187]
	global_store_dwordx4 v169, v[8:11], s[2:3] offset:576 sc1
	s_waitcnt vmcnt(14)
	v_pk_fma_f32 v[16:17], v[16:17], v[140:141], v[188:189]
	v_pk_fma_f32 v[18:19], v[18:19], v[142:143], v[190:191]
	global_store_dwordx4 v170, v[16:19], s[2:3] sc1
	s_waitcnt vmcnt(13)
	v_pk_fma_f32 v[12:13], v[12:13], v[136:137], v[192:193]
	v_pk_fma_f32 v[14:15], v[14:15], v[138:139], v[194:195]
	global_store_dwordx4 v170, v[12:15], s[2:3] offset:64 sc1
	s_waitcnt vmcnt(12)
	v_pk_fma_f32 v[4:5], v[4:5], v[132:133], v[196:197]
	v_pk_fma_f32 v[6:7], v[6:7], v[134:135], v[198:199]
	global_store_dwordx4 v170, v[4:7], s[2:3] offset:512 sc1
	s_waitcnt vmcnt(11)
	v_pk_fma_f32 v[0:1], v[0:1], v[128:129], v[200:201]
	v_pk_fma_f32 v[2:3], v[2:3], v[130:131], v[202:203]
	global_store_dwordx4 v170, v[0:3], s[2:3] offset:576 sc1
	s_cbranch_vccnz .LBB0_566
	s_andn2_b64 vcc, exec, s[4:5]
	s_cbranch_vccnz .LBB0_565
	s_barrier
	s_branch .LBB0_565

.LBB0_818:
	s_ashr_i32 s26, s57, 31
	s_lshr_b32 s26, s26, 29
	s_add_i32 s26, s57, s26
	s_ashr_i32 s26, s26, 3
	v_lshl_add_u32 v160, s57, 8, v162
	v_lshl_or_b32 v64, s58, 8, v164
	s_mul_hi_i32 s27, s26, 0x6000
	s_mulk_i32 s26, 0x6000
	v_ashrrev_i32_e32 v161, 31, v160
	s_add_u32 s26, s45, s26
	v_ashrrev_i32_e32 v65, 31, v64
	v_lshlrev_b64 v[156:157], 12, v[160:161]
	s_addc_u32 s27, s46, s27
	v_lshlrev_b64 v[158:159], 2, v[64:65]
	v_lshl_add_u64 v[156:157], s[2:3], 0, v[156:157]
	v_lshl_add_u64 v[64:65], s[26:27], 0, v[158:159]
	v_lshl_add_u64 v[156:157], v[156:157], 0, v[158:159]
	flat_load_dwordx4 v[128:131], v[64:65]
	flat_load_dwordx4 v[116:119], v[64:65] offset:64
	flat_load_dwordx4 v[108:111], v[64:65] offset:512
	s_nop 0
	flat_load_dwordx4 v[64:67], v[64:65] offset:576
	s_mov_b64 s[26:27], -1
	flat_load_dwordx4 v[168:171], v[156:157]
	s_waitcnt vmcnt(0) lgkmcnt(0)
	v_pk_fma_f32 v[142:143], v[142:143], v[130:131], v[170:171]
	v_pk_fma_f32 v[140:141], v[140:141], v[128:129], v[168:169]
	global_store_dwordx4 v[156:157], v[140:143], off nt
	flat_load_dwordx4 v[140:143], v[156:157] offset:64
	s_waitcnt vmcnt(0) lgkmcnt(0)
	v_pk_fma_f32 v[138:139], v[138:139], v[118:119], v[142:143]
	v_pk_fma_f32 v[136:137], v[136:137], v[116:117], v[140:141]
	global_store_dwordx4 v[156:157], v[136:139], off offset:64 nt
	flat_load_dwordx4 v[136:139], v[156:157] offset:512
	s_waitcnt vmcnt(0) lgkmcnt(0)
	v_pk_fma_f32 v[134:135], v[134:135], v[110:111], v[138:139]
	v_pk_fma_f32 v[132:133], v[132:133], v[108:109], v[136:137]
	global_store_dwordx4 v[156:157], v[132:135], off offset:512 nt
	flat_load_dwordx4 v[132:135], v[156:157] offset:576
	s_waitcnt vmcnt(0) lgkmcnt(0)
	v_pk_fma_f32 v[126:127], v[126:127], v[66:67], v[134:135]
	v_pk_fma_f32 v[124:125], v[124:125], v[64:65], v[132:133]
	global_store_dwordx4 v[156:157], v[124:127], off offset:576 nt
	s_nop 1
	v_or_b32_e32 v124, 16, v160
	v_ashrrev_i32_e32 v125, 31, v124
	v_lshlrev_b64 v[124:125], 12, v[124:125]
	v_lshl_add_u64 v[124:125], s[2:3], 0, v[124:125]
	v_lshl_add_u64 v[132:133], v[124:125], 0, v[158:159]
	flat_load_dwordx4 v[124:127], v[132:133]
	s_waitcnt vmcnt(0) lgkmcnt(0)
	v_pk_fma_f32 v[122:123], v[122:123], v[130:131], v[126:127]
	v_pk_fma_f32 v[120:121], v[120:121], v[128:129], v[124:125]
	global_store_dwordx4 v[132:133], v[120:123], off nt
	flat_load_dwordx4 v[120:123], v[132:133] offset:64
	s_waitcnt vmcnt(0) lgkmcnt(0)
	v_pk_fma_f32 v[114:115], v[114:115], v[118:119], v[122:123]
	v_pk_fma_f32 v[112:113], v[112:113], v[116:117], v[120:121]
	global_store_dwordx4 v[132:133], v[112:115], off offset:64 nt
	flat_load_dwordx4 v[112:115], v[132:133] offset:512
	s_waitcnt vmcnt(0) lgkmcnt(0)
	v_pk_fma_f32 v[106:107], v[106:107], v[110:111], v[114:115]
	v_pk_fma_f32 v[104:105], v[104:105], v[108:109], v[112:113]
	global_store_dwordx4 v[132:133], v[104:107], off offset:512 nt
	flat_load_dwordx4 v[104:107], v[132:133] offset:576
	s_waitcnt vmcnt(0) lgkmcnt(0)
	v_pk_fma_f32 v[102:103], v[102:103], v[66:67], v[106:107]
	v_pk_fma_f32 v[100:101], v[100:101], v[64:65], v[104:105]
	global_store_dwordx4 v[132:133], v[100:103], off offset:576 nt
	s_nop 1
	v_or_b32_e32 v100, 32, v160
	v_ashrrev_i32_e32 v101, 31, v100
	v_lshlrev_b64 v[100:101], 12, v[100:101]
	v_lshl_add_u64 v[100:101], s[2:3], 0, v[100:101]
	v_lshl_add_u64 v[104:105], v[100:101], 0, v[158:159]
	flat_load_dwordx4 v[100:103], v[104:105]
	s_waitcnt vmcnt(0) lgkmcnt(0)
	v_pk_fma_f32 v[98:99], v[98:99], v[130:131], v[102:103]
	v_pk_fma_f32 v[96:97], v[96:97], v[128:129], v[100:101]
	global_store_dwordx4 v[104:105], v[96:99], off nt
	flat_load_dwordx4 v[96:99], v[104:105] offset:64
	s_waitcnt vmcnt(0) lgkmcnt(0)
	v_pk_fma_f32 v[94:95], v[94:95], v[118:119], v[98:99]
	v_pk_fma_f32 v[92:93], v[92:93], v[116:117], v[96:97]
	global_store_dwordx4 v[104:105], v[92:95], off offset:64 nt
	flat_load_dwordx4 v[92:95], v[104:105] offset:512
	s_waitcnt vmcnt(0) lgkmcnt(0)
	v_pk_fma_f32 v[90:91], v[90:91], v[110:111], v[94:95]
	v_pk_fma_f32 v[88:89], v[88:89], v[108:109], v[92:93]
	global_store_dwordx4 v[104:105], v[88:91], off offset:512 nt
	flat_load_dwordx4 v[88:91], v[104:105] offset:576
	s_waitcnt vmcnt(0) lgkmcnt(0)
	v_pk_fma_f32 v[86:87], v[86:87], v[66:67], v[90:91]
	v_pk_fma_f32 v[84:85], v[84:85], v[64:65], v[88:89]
	global_store_dwordx4 v[104:105], v[84:87], off offset:576 nt
	s_nop 1
	v_or_b32_e32 v84, 48, v160
	v_ashrrev_i32_e32 v85, 31, v84
	v_lshlrev_b64 v[84:85], 12, v[84:85]
	v_lshl_add_u64 v[84:85], s[2:3], 0, v[84:85]
	v_lshl_add_u64 v[88:89], v[84:85], 0, v[158:159]
	flat_load_dwordx4 v[84:87], v[88:89]
	s_waitcnt vmcnt(0) lgkmcnt(0)
	v_pk_fma_f32 v[82:83], v[82:83], v[130:131], v[86:87]
	v_pk_fma_f32 v[80:81], v[80:81], v[128:129], v[84:85]
	global_store_dwordx4 v[88:89], v[80:83], off nt
	flat_load_dwordx4 v[80:83], v[88:89] offset:64
	s_waitcnt vmcnt(0) lgkmcnt(0)
	v_pk_fma_f32 v[78:79], v[78:79], v[118:119], v[82:83]
	v_pk_fma_f32 v[76:77], v[76:77], v[116:117], v[80:81]
	global_store_dwordx4 v[88:89], v[76:79], off offset:64 nt
	flat_load_dwordx4 v[76:79], v[88:89] offset:512
	s_waitcnt vmcnt(0) lgkmcnt(0)
	v_pk_fma_f32 v[74:75], v[74:75], v[110:111], v[78:79]
	v_pk_fma_f32 v[72:73], v[72:73], v[108:109], v[76:77]
	global_store_dwordx4 v[88:89], v[72:75], off offset:512 nt
	flat_load_dwordx4 v[72:75], v[88:89] offset:576
	s_waitcnt vmcnt(0) lgkmcnt(0)
	v_pk_fma_f32 v[70:71], v[70:71], v[66:67], v[74:75]
	v_add_co_u32_e32 v74, vcc, s51, v156
	v_pk_fma_f32 v[68:69], v[68:69], v[64:65], v[72:73]
	s_nop 0
	v_addc_co_u32_e32 v75, vcc, 0, v157, vcc
	global_store_dwordx4 v[88:89], v[68:71], off offset:576 nt
	flat_load_dwordx4 v[68:71], v[74:75]
	v_lshl_add_u64 v[72:73], v[156:157], 0, s[12:13]
	s_waitcnt vmcnt(0) lgkmcnt(0)
	v_pk_fma_f32 v[62:63], v[62:63], v[130:131], v[70:71]
	v_pk_fma_f32 v[60:61], v[60:61], v[128:129], v[68:69]
	global_store_dwordx4 v[74:75], v[60:63], off nt
	flat_load_dwordx4 v[60:63], v[72:73] offset:64
	s_waitcnt vmcnt(0) lgkmcnt(0)
	v_pk_fma_f32 v[58:59], v[58:59], v[118:119], v[62:63]
	v_pk_fma_f32 v[56:57], v[56:57], v[116:117], v[60:61]
	global_store_dwordx4 v[72:73], v[56:59], off offset:64 nt
	flat_load_dwordx4 v[56:59], v[72:73] offset:512
	s_waitcnt vmcnt(0) lgkmcnt(0)
	v_pk_fma_f32 v[54:55], v[54:55], v[110:111], v[58:59]
	v_pk_fma_f32 v[52:53], v[52:53], v[108:109], v[56:57]
	global_store_dwordx4 v[72:73], v[52:55], off offset:512 nt
	flat_load_dwordx4 v[52:55], v[72:73] offset:576
	s_waitcnt vmcnt(0) lgkmcnt(0)
	v_pk_fma_f32 v[50:51], v[50:51], v[66:67], v[54:55]
	v_add_co_u32_e32 v54, vcc, s52, v156
	v_pk_fma_f32 v[48:49], v[48:49], v[64:65], v[52:53]
	s_nop 0
	v_addc_co_u32_e32 v55, vcc, 0, v157, vcc
	global_store_dwordx4 v[72:73], v[48:51], off offset:576 nt
	flat_load_dwordx4 v[48:51], v[54:55]
	v_lshl_add_u64 v[52:53], v[156:157], 0, s[14:15]
	s_waitcnt vmcnt(0) lgkmcnt(0)
	v_pk_fma_f32 v[46:47], v[46:47], v[130:131], v[50:51]
	v_pk_fma_f32 v[44:45], v[44:45], v[128:129], v[48:49]
	global_store_dwordx4 v[54:55], v[44:47], off nt
	flat_load_dwordx4 v[44:47], v[52:53] offset:64
	s_waitcnt vmcnt(0) lgkmcnt(0)
	v_pk_fma_f32 v[42:43], v[42:43], v[118:119], v[46:47]
	v_pk_fma_f32 v[40:41], v[40:41], v[116:117], v[44:45]
	global_store_dwordx4 v[52:53], v[40:43], off offset:64 nt
	flat_load_dwordx4 v[40:43], v[52:53] offset:512
	s_waitcnt vmcnt(0) lgkmcnt(0)
	v_pk_fma_f32 v[38:39], v[38:39], v[110:111], v[42:43]
	v_pk_fma_f32 v[36:37], v[36:37], v[108:109], v[40:41]
	global_store_dwordx4 v[52:53], v[36:39], off offset:512 nt
	flat_load_dwordx4 v[36:39], v[52:53] offset:576
	s_waitcnt vmcnt(0) lgkmcnt(0)
	v_pk_fma_f32 v[34:35], v[34:35], v[66:67], v[38:39]
	v_add_co_u32_e32 v38, vcc, s53, v156
	v_pk_fma_f32 v[32:33], v[32:33], v[64:65], v[36:37]
	s_nop 0
	v_addc_co_u32_e32 v39, vcc, 0, v157, vcc
	global_store_dwordx4 v[52:53], v[32:35], off offset:576 nt
	flat_load_dwordx4 v[32:35], v[38:39]
	v_lshl_add_u64 v[36:37], v[156:157], 0, s[16:17]
	s_waitcnt vmcnt(0) lgkmcnt(0)
	v_pk_fma_f32 v[30:31], v[30:31], v[130:131], v[34:35]
	v_pk_fma_f32 v[28:29], v[28:29], v[128:129], v[32:33]
	global_store_dwordx4 v[38:39], v[28:31], off nt
	flat_load_dwordx4 v[28:31], v[36:37] offset:64
	s_waitcnt vmcnt(0) lgkmcnt(0)
	v_pk_fma_f32 v[26:27], v[26:27], v[118:119], v[30:31]
	v_pk_fma_f32 v[24:25], v[24:25], v[116:117], v[28:29]
	global_store_dwordx4 v[36:37], v[24:27], off offset:64 nt
	flat_load_dwordx4 v[24:27], v[36:37] offset:512
	s_waitcnt vmcnt(0) lgkmcnt(0)
	v_pk_fma_f32 v[22:23], v[22:23], v[110:111], v[26:27]
	v_pk_fma_f32 v[20:21], v[20:21], v[108:109], v[24:25]
	global_store_dwordx4 v[36:37], v[20:23], off offset:512 nt
	flat_load_dwordx4 v[20:23], v[36:37] offset:576
	s_waitcnt vmcnt(0) lgkmcnt(0)
	v_pk_fma_f32 v[18:19], v[18:19], v[66:67], v[22:23]
	v_add_co_u32_e32 v22, vcc, s54, v156
	v_pk_fma_f32 v[16:17], v[16:17], v[64:65], v[20:21]
	s_nop 0
	v_addc_co_u32_e32 v23, vcc, 0, v157, vcc
	global_store_dwordx4 v[36:37], v[16:19], off offset:576 nt
	flat_load_dwordx4 v[18:21], v[22:23]
	s_andn2_b64 vcc, exec, s[0:1]
	v_lshl_add_u64 v[16:17], v[156:157], 0, s[4:5]
	s_waitcnt vmcnt(0) lgkmcnt(0)
	v_pk_fma_f32 v[14:15], v[14:15], v[130:131], v[20:21]
	v_pk_fma_f32 v[12:13], v[12:13], v[128:129], v[18:19]
	global_store_dwordx4 v[22:23], v[12:15], off nt
	flat_load_dwordx4 v[12:15], v[16:17] offset:64
	s_waitcnt vmcnt(0) lgkmcnt(0)
	v_pk_fma_f32 v[10:11], v[10:11], v[118:119], v[14:15]
	v_pk_fma_f32 v[8:9], v[8:9], v[116:117], v[12:13]
	global_store_dwordx4 v[16:17], v[8:11], off offset:64 nt
	flat_load_dwordx4 v[8:11], v[16:17] offset:512
	s_waitcnt vmcnt(0) lgkmcnt(0)
	v_pk_fma_f32 v[6:7], v[6:7], v[110:111], v[10:11]
	v_pk_fma_f32 v[4:5], v[4:5], v[108:109], v[8:9]
	global_store_dwordx4 v[16:17], v[4:7], off offset:512 nt
	flat_load_dwordx4 v[4:7], v[16:17] offset:576
	s_waitcnt vmcnt(0) lgkmcnt(0)
	v_pk_fma_f32 v[2:3], v[2:3], v[66:67], v[6:7]
	v_pk_fma_f32 v[0:1], v[0:1], v[64:65], v[4:5]
	global_store_dwordx4 v[16:17], v[0:3], off offset:576 nt
	s_cbranch_vccnz .LBB0_807
	s_andn2_b64 vcc, exec, s[6:7]
	s_cbranch_vccnz .LBB0_806
	s_barrier
	s_branch .LBB0_806
